# first K-iteration of the 4 non-strip GEMM loops peeled: first-touch MFMAs take SrcC=0, the 128 accumulator-zeroing v_mov per unit are gone (on top of k-chain + no setprio)
# speedup vs baseline: 1.0220x; 1.0057x over previous
; #define PG8_STAGE(bufoff, gbase, voff) do { _Pragma("unroll") for (int _i = 0; _i < 2; ++_i) \
;         __builtin_amdgcn_global_load_lds((const GAS unsigned*)((const GAS char*)(gbase) + (voff)[_i]), (PG8_LAS unsigned*)(lds + (bufoff) + ldsw + _i * 8192), 16, 0, 0); } while (0)
; #define PG8_LDA(dst, b, h) do { _Pragma("unroll") for (int m = 0; m < 4; ++m) _Pragma("unroll") for (int k = 0; k < 2; ++k) dst[m][k] = *(const PG8_LAS bf16x8*)(lds + PG8_SA(b, h) + aoff + m * 2048 + k * 1024); } while (0)
; #define PG8_LDB(dst, b, h) do { _Pragma("unroll") for (int n = 0; n < 2; ++n) _Pragma("unroll") for (int k = 0; k < 2; ++k) dst[n][k] = *(const PG8_LAS bf16x8*)(lds + PG8_SB(b, h) + boff + n * 2048 + k * 1024); } while (0)
; #define PG8_MMA(ai, bj, At, Bt) do { __builtin_amdgcn_s_setprio(1); _Pragma("unroll") for (int m = 0; m < 4; ++m) _Pragma("unroll") for (int n = 0; n < 2; ++n) _Pragma("unroll") for (int k = 0; k < 2; ++k) \
;         acc[ai][bj][m][n] = __builtin_amdgcn_mfma_f32_16x16x32_bf16(Bt[n][k], At[m][k], acc[ai][bj][m][n], 0, 0, 0); __builtin_amdgcn_s_setprio(0); } while (0)
; #define PG8_WAIT_V(n) asm volatile("s_waitcnt vmcnt(" #n ")" ::: "memory")
; #define PG8_WAIT_L(n) asm volatile("s_waitcnt lgkmcnt(" #n ")" ::: "memory")
; #define PG8_BAR __builtin_amdgcn_s_barrier()
; #define PG8_SCHED __builtin_amdgcn_sched_barrier(0)
; #define PG8_WAIT_V(n) asm volatile("s_waitcnt vmcnt(" #n ")" ::: "memory")
; template <class Epi, class Sched, bool ALIGN_EPI = false, bool SP2 = false>
; __device__ __forceinline__ void gemm_phase(PG8_LAS unsigned char* lds, PG8_LAS unsigned char* pf, const Gemm g, const Sched& S, const Epi& E, int wv) {
;     ...
;             PG8_LDB(B0, 0, 0); PG8_LDB(B1, 0, 1); PG8_SCHED; PG8_LDA(At, 0, 0); PG8_STAGE(PG8_SA(1, 1), a1 + (Sched::SPLIT ? hsA : (long)hstepA), voffA);
;             PG8_WAIT_V(8); PG8_WAIT_L(0); PG8_BAR; PG8_MMA(0, 0, At, B0); PG8_MMA(0, 1, At, B1); PG8_BAR; PG8_SCHED;
;             PG8_LDA(At, 0, 1); PG8_STAGE(PG8_SB(0, 0), b2, voffB); PG8_STAGE(PG8_SB(0, 1), b2 + hstepB, voffB); PG8_STAGE(PG8_SA(0, 0), a2, voffA);
;     ...
;         for (int a = 0; a < 2; ++a)
; #pragma unroll
;             for (int b = 0; b < 2; ++b)
; #pragma unroll
;                 for (int m = 0; m < 4; ++m)
; #pragma unroll
;                     for (int n = 0; n < 2; ++n) acc[a][b][m][n] = (f32x4){0.f, 0.f, 0.f, 0.f};
.LBB0_1185:
	s_ashr_i32 s11, s10, 31
	s_lshl_b64 s[20:21], s[10:11], 18
	s_add_u32 s40, s69, s20
	s_addc_u32 s41, s72, s21
	s_and_b64 s[20:21], s[36:37], exec
	s_cselect_b32 s5, s41, s15
	s_cselect_b32 s11, s40, s14
	s_add_u32 s13, s14, 0x100
	s_addc_u32 s20, s15, 0
	s_add_u32 s14, s42, 0x80080
	s_addc_u32 s15, s43, 0
	s_mov_b32 s21, -2
	s_waitcnt lgkmcnt(0)
.Lpeel_pg:
	s_add_u32 s22, s14, 0xfff80080
	s_addc_u32 s23, s15, -1
	s_add_i32 s24, 0, 0x10000
	s_cmp_eq_u32 s21, 4
	s_cselect_b32 s29, s39, s23
	s_cselect_b32 s28, s38, s22
	s_cselect_b32 s37, s5, s20
	s_cselect_b32 s36, s11, s13
	s_add_i32 s25, 0, 0x14000
	v_add_u32_e32 v140, s24, v204
	v_add_u32_e32 v156, s25, v204
	ds_read_b128 v[120:123], v140
	ds_read_b128 v[124:127], v140 offset:1024
	ds_read_b128 v[136:139], v140 offset:2048
	ds_read_b128 v[140:143], v140 offset:3072
	ds_read_b128 v[144:147], v156
	ds_read_b128 v[148:151], v156 offset:1024
	ds_read_b128 v[152:155], v156 offset:2048
	ds_read_b128 v[156:159], v156 offset:3072
	v_lshl_add_u64 v[214:215], s[14:15], 0, v[172:173]
	s_add_i32 m0, s18, 0xc000
	ds_read_b128 v[174:177], v205
	ds_read_b128 v[178:181], v205 offset:1024
	ds_read_b128 v[182:185], v205 offset:2048
	ds_read_b128 v[186:189], v205 offset:3072
	ds_read_b128 v[190:193], v205 offset:4096
	ds_read_b128 v[194:197], v205 offset:5120
	ds_read_b128 v[198:201], v205 offset:6144
	ds_read_b128 v[206:209], v205 offset:7168
	global_load_lds_dwordx4 v[214:215], off
	v_lshl_add_u64 v[214:215], s[14:15], 0, v[170:171]
	s_add_i32 m0, s18, 0xe000
	s_nop 0
	global_load_lds_dwordx4 v[214:215], off
	s_waitcnt vmcnt(8)
	s_waitcnt lgkmcnt(0)
	s_barrier
	s_waitcnt lgkmcnt(0)
	v_mfma_f32_16x16x32_bf16 v[132:135], v[120:123], v[174:177], 0
	v_mfma_f32_16x16x32_bf16 v[132:135], v[124:127], v[178:181], v[132:135]
	v_mfma_f32_16x16x32_bf16 v[128:131], v[136:139], v[174:177], 0
	v_mfma_f32_16x16x32_bf16 v[128:131], v[140:143], v[178:181], v[128:131]
	v_mfma_f32_16x16x32_bf16 v[116:119], v[120:123], v[182:185], 0
	v_mfma_f32_16x16x32_bf16 v[116:119], v[124:127], v[186:189], v[116:119]
	v_mfma_f32_16x16x32_bf16 v[112:115], v[136:139], v[182:185], 0
	v_mfma_f32_16x16x32_bf16 v[112:115], v[140:143], v[186:189], v[112:115]
	v_mfma_f32_16x16x32_bf16 v[108:111], v[120:123], v[190:193], 0
	v_mfma_f32_16x16x32_bf16 v[108:111], v[124:127], v[194:197], v[108:111]
	v_mfma_f32_16x16x32_bf16 v[104:107], v[136:139], v[190:193], 0
	v_mfma_f32_16x16x32_bf16 v[104:107], v[140:143], v[194:197], v[104:107]
	v_mfma_f32_16x16x32_bf16 v[100:103], v[120:123], v[198:201], 0
	v_mfma_f32_16x16x32_bf16 v[100:103], v[124:127], v[206:209], v[100:103]
	v_mfma_f32_16x16x32_bf16 v[96:99], v[136:139], v[198:201], 0
	v_mfma_f32_16x16x32_bf16 v[96:99], v[140:143], v[206:209], v[96:99]
	v_mfma_f32_16x16x32_bf16 v[60:63], v[144:147], v[174:177], 0
	v_mfma_f32_16x16x32_bf16 v[60:63], v[148:151], v[178:181], v[60:63]
	v_mfma_f32_16x16x32_bf16 v[56:59], v[152:155], v[174:177], 0
	v_mfma_f32_16x16x32_bf16 v[56:59], v[156:159], v[178:181], v[56:59]
	v_mfma_f32_16x16x32_bf16 v[52:55], v[144:147], v[182:185], 0
	v_mfma_f32_16x16x32_bf16 v[52:55], v[148:151], v[186:189], v[52:55]
	v_mfma_f32_16x16x32_bf16 v[48:51], v[152:155], v[182:185], 0
	v_mfma_f32_16x16x32_bf16 v[48:51], v[156:159], v[186:189], v[48:51]
	v_mfma_f32_16x16x32_bf16 v[44:47], v[144:147], v[190:193], 0
	v_mfma_f32_16x16x32_bf16 v[44:47], v[148:151], v[194:197], v[44:47]
	v_mfma_f32_16x16x32_bf16 v[40:43], v[152:155], v[190:193], 0
	v_mfma_f32_16x16x32_bf16 v[40:43], v[156:159], v[194:197], v[40:43]
	v_mfma_f32_16x16x32_bf16 v[36:39], v[144:147], v[198:201], 0
	v_mfma_f32_16x16x32_bf16 v[36:39], v[148:151], v[206:209], v[36:39]
	v_mfma_f32_16x16x32_bf16 v[32:35], v[152:155], v[198:201], 0
	v_mfma_f32_16x16x32_bf16 v[32:35], v[156:159], v[206:209], v[32:35]
	s_barrier
	s_add_i32 s22, s24, s81
	v_lshl_add_u64 v[214:215], s[36:37], 0, v[164:165]
	s_mov_b32 m0, s22
	ds_read_b128 v[174:177], v205 offset:16384
	ds_read_b128 v[178:181], v205 offset:17408
	ds_read_b128 v[182:185], v205 offset:18432
	ds_read_b128 v[186:189], v205 offset:19456
	ds_read_b128 v[190:193], v205 offset:20480
	ds_read_b128 v[194:197], v205 offset:21504
	ds_read_b128 v[198:201], v205 offset:22528
	ds_read_b128 v[206:209], v205 offset:23552
	global_load_lds_dwordx4 v[214:215], off
	s_add_i32 m0, s22, 0x2000
	s_add_u32 s22, s36, 0x20000
	v_lshl_add_u64 v[216:217], s[36:37], 0, v[168:169]
	s_addc_u32 s23, s37, 0
	s_add_i32 s24, s25, s81
	global_load_lds_dwordx4 v[216:217], off
	v_lshl_add_u64 v[218:219], s[22:23], 0, v[164:165]
	s_mov_b32 m0, s24
	v_lshl_add_u64 v[220:221], s[28:29], 0, v[166:167]
	global_load_lds_dwordx4 v[218:219], off
	v_lshl_add_u64 v[218:219], s[22:23], 0, v[168:169]
	s_add_i32 m0, s24, 0x2000
	s_nop 0
	global_load_lds_dwordx4 v[218:219], off
	v_lshl_add_u64 v[218:219], s[28:29], 0, v[162:163]
	s_mov_b32 m0, s18
	s_nop 0
	global_load_lds_dwordx4 v[218:219], off
	s_mov_b32 m0, s19
	s_nop 0
	global_load_lds_dwordx4 v[220:221], off
	s_waitcnt vmcnt(8)
	s_waitcnt lgkmcnt(0)
	s_barrier
; #define PG8_STAGE(bufoff, gbase, voff) do { _Pragma("unroll") for (int _i = 0; _i < 2; ++_i) \
;         __builtin_amdgcn_global_load_lds((const GAS unsigned*)((const GAS char*)(gbase) + (voff)[_i]), (PG8_LAS unsigned*)(lds + (bufoff) + ldsw + _i * 8192), 16, 0, 0); } while (0)
; #define PG8_LDA(dst, b, h) do { _Pragma("unroll") for (int m = 0; m < 4; ++m) _Pragma("unroll") for (int k = 0; k < 2; ++k) dst[m][k] = *(const PG8_LAS bf16x8*)(lds + PG8_SA(b, h) + aoff + m * 2048 + k * 1024); } while (0)
; #define PG8_LDB(dst, b, h) do { _Pragma("unroll") for (int n = 0; n < 2; ++n) _Pragma("unroll") for (int k = 0; k < 2; ++k) dst[n][k] = *(const PG8_LAS bf16x8*)(lds + PG8_SB(b, h) + boff + n * 2048 + k * 1024); } while (0)
; #define PG8_MMA(ai, bj, At, Bt) do { __builtin_amdgcn_s_setprio(1); _Pragma("unroll") for (int m = 0; m < 4; ++m) _Pragma("unroll") for (int n = 0; n < 2; ++n) _Pragma("unroll") for (int k = 0; k < 2; ++k) \
;         acc[ai][bj][m][n] = __builtin_amdgcn_mfma_f32_16x16x32_bf16(Bt[n][k], At[m][k], acc[ai][bj][m][n], 0, 0, 0); __builtin_amdgcn_s_setprio(0); } while (0)
; #define PG8_WAIT_V(n) asm volatile("s_waitcnt vmcnt(" #n ")" ::: "memory")
; #define PG8_WAIT_L(n) asm volatile("s_waitcnt lgkmcnt(" #n ")" ::: "memory")
; #define PG8_BAR __builtin_amdgcn_s_barrier()
; #define PG8_SCHED __builtin_amdgcn_sched_barrier(0)
; #define PG8_STAGE(bufoff, gbase, voff) do { _Pragma("unroll") for (int _i = 0; _i < 2; ++_i) \
;         __builtin_amdgcn_global_load_lds((const GAS unsigned*)((const GAS char*)(gbase) + (voff)[_i]), (PG8_LAS unsigned*)(lds + (bufoff) + ldsw + _i * 8192), 16, 0, 0); } while (0)
; #define PG8_BAR __builtin_amdgcn_s_barrier()
; template <class Epi, class Sched, bool ALIGN_EPI = false, bool SP2 = false>
; __device__ __forceinline__ void gemm_phase(PG8_LAS unsigned char* lds, PG8_LAS unsigned char* pf, const Gemm g, const Sched& S, const Epi& E, int wv) {
;     ...
;             PG8_WAIT_V(8); PG8_WAIT_L(0); PG8_BAR; PG8_MMA(1, 0, At, B0); PG8_MMA(1, 1, At, B1); PG8_BAR; PG8_SCHED;
;             PG8_LDB(B0, 1, 0); PG8_LDB(B1, 1, 1); PG8_SCHED; PG8_LDA(At, 1, 0); PG8_STAGE(PG8_SA(0, 1), a2 + (Sched::SPLIT ? ((last && has_next) ? (nxt.kh > 0 ? -(long)hstepA : (long)hstepA) : hsA) : (long)hstepA), voffA);
;             PG8_WAIT_V(8); PG8_WAIT_L(0); PG8_BAR; PG8_MMA(0, 0, At, B0); PG8_MMA(0, 1, At, B1); PG8_BAR; PG8_SCHED;
	s_waitcnt lgkmcnt(0)
	v_mfma_f32_16x16x32_bf16 v[92:95], v[120:123], v[174:177], 0
	v_mfma_f32_16x16x32_bf16 v[92:95], v[124:127], v[178:181], v[92:95]
	v_mfma_f32_16x16x32_bf16 v[88:91], v[136:139], v[174:177], 0
	v_mfma_f32_16x16x32_bf16 v[88:91], v[140:143], v[178:181], v[88:91]
	v_mfma_f32_16x16x32_bf16 v[84:87], v[120:123], v[182:185], 0
	v_mfma_f32_16x16x32_bf16 v[84:87], v[124:127], v[186:189], v[84:87]
	v_mfma_f32_16x16x32_bf16 v[80:83], v[136:139], v[182:185], 0
	v_mfma_f32_16x16x32_bf16 v[80:83], v[140:143], v[186:189], v[80:83]
	v_mfma_f32_16x16x32_bf16 v[76:79], v[120:123], v[190:193], 0
	v_mfma_f32_16x16x32_bf16 v[76:79], v[124:127], v[194:197], v[76:79]
	v_mfma_f32_16x16x32_bf16 v[72:75], v[136:139], v[190:193], 0
	v_mfma_f32_16x16x32_bf16 v[72:75], v[140:143], v[194:197], v[72:75]
	v_mfma_f32_16x16x32_bf16 v[68:71], v[120:123], v[198:201], 0
	v_mfma_f32_16x16x32_bf16 v[68:71], v[124:127], v[206:209], v[68:71]
	v_mfma_f32_16x16x32_bf16 v[64:67], v[136:139], v[198:201], 0
	v_mfma_f32_16x16x32_bf16 v[64:67], v[140:143], v[206:209], v[64:67]
	v_mfma_f32_16x16x32_bf16 v[28:31], v[144:147], v[174:177], 0
	v_mfma_f32_16x16x32_bf16 v[28:31], v[148:151], v[178:181], v[28:31]
	v_mfma_f32_16x16x32_bf16 v[24:27], v[152:155], v[174:177], 0
	v_mfma_f32_16x16x32_bf16 v[24:27], v[156:159], v[178:181], v[24:27]
	v_mfma_f32_16x16x32_bf16 v[20:23], v[144:147], v[182:185], 0
	v_mfma_f32_16x16x32_bf16 v[20:23], v[148:151], v[186:189], v[20:23]
	v_mfma_f32_16x16x32_bf16 v[16:19], v[152:155], v[182:185], 0
	v_mfma_f32_16x16x32_bf16 v[16:19], v[156:159], v[186:189], v[16:19]
	v_mfma_f32_16x16x32_bf16 v[12:15], v[144:147], v[190:193], 0
	v_mfma_f32_16x16x32_bf16 v[12:15], v[148:151], v[194:197], v[12:15]
	v_mfma_f32_16x16x32_bf16 v[8:11], v[152:155], v[190:193], 0
	v_mfma_f32_16x16x32_bf16 v[8:11], v[156:159], v[194:197], v[8:11]
	v_mfma_f32_16x16x32_bf16 v[4:7], v[144:147], v[198:201], 0
	v_mfma_f32_16x16x32_bf16 v[4:7], v[148:151], v[206:209], v[4:7]
	v_mfma_f32_16x16x32_bf16 v[0:3], v[152:155], v[198:201], 0
	v_mfma_f32_16x16x32_bf16 v[0:3], v[156:159], v[206:209], v[0:3]
	s_barrier
	s_add_i32 s24, 0, 0x18000
	s_add_i32 s25, 0, 0x1c000
	v_add_u32_e32 v140, s24, v204
	v_add_u32_e32 v156, s25, v204
	ds_read_b128 v[120:123], v140
	ds_read_b128 v[124:127], v140 offset:1024
	ds_read_b128 v[136:139], v140 offset:2048
	ds_read_b128 v[140:143], v140 offset:3072
	ds_read_b128 v[144:147], v156
	ds_read_b128 v[148:151], v156 offset:1024
	ds_read_b128 v[152:155], v156 offset:2048
	ds_read_b128 v[156:159], v156 offset:3072
	s_add_u32 s22, s28, 0x80000
	s_addc_u32 s23, s29, 0
	s_mov_b32 m0, s27
	v_lshl_add_u64 v[222:223], s[22:23], 0, v[162:163]
	ds_read_b128 v[174:177], v205 offset:32768
	ds_read_b128 v[178:181], v205 offset:33792
	ds_read_b128 v[182:185], v205 offset:34816
	ds_read_b128 v[186:189], v205 offset:35840
	ds_read_b128 v[190:193], v205 offset:36864
	ds_read_b128 v[194:197], v205 offset:37888
	ds_read_b128 v[198:201], v205 offset:38912
	ds_read_b128 v[206:209], v205 offset:39936
	global_load_lds_dwordx4 v[222:223], off
	v_lshl_add_u64 v[222:223], s[22:23], 0, v[166:167]
	s_mov_b32 m0, s52
	s_nop 0
	global_load_lds_dwordx4 v[222:223], off
	s_waitcnt vmcnt(8)
	s_waitcnt lgkmcnt(0)
	s_barrier
	s_waitcnt lgkmcnt(0)
	v_mfma_f32_16x16x32_bf16 v[132:135], v[120:123], v[174:177], v[132:135]
	v_mfma_f32_16x16x32_bf16 v[132:135], v[124:127], v[178:181], v[132:135]
	v_mfma_f32_16x16x32_bf16 v[128:131], v[136:139], v[174:177], v[128:131]
	v_mfma_f32_16x16x32_bf16 v[128:131], v[140:143], v[178:181], v[128:131]
	v_mfma_f32_16x16x32_bf16 v[116:119], v[120:123], v[182:185], v[116:119]
	v_mfma_f32_16x16x32_bf16 v[116:119], v[124:127], v[186:189], v[116:119]
	v_mfma_f32_16x16x32_bf16 v[112:115], v[136:139], v[182:185], v[112:115]
	v_mfma_f32_16x16x32_bf16 v[112:115], v[140:143], v[186:189], v[112:115]
	v_mfma_f32_16x16x32_bf16 v[108:111], v[120:123], v[190:193], v[108:111]
	v_mfma_f32_16x16x32_bf16 v[108:111], v[124:127], v[194:197], v[108:111]
	v_mfma_f32_16x16x32_bf16 v[104:107], v[136:139], v[190:193], v[104:107]
	v_mfma_f32_16x16x32_bf16 v[104:107], v[140:143], v[194:197], v[104:107]
	v_mfma_f32_16x16x32_bf16 v[100:103], v[120:123], v[198:201], v[100:103]
	v_mfma_f32_16x16x32_bf16 v[100:103], v[124:127], v[206:209], v[100:103]
	v_mfma_f32_16x16x32_bf16 v[96:99], v[136:139], v[198:201], v[96:99]
	v_mfma_f32_16x16x32_bf16 v[96:99], v[140:143], v[206:209], v[96:99]
	v_mfma_f32_16x16x32_bf16 v[60:63], v[144:147], v[174:177], v[60:63]
	v_mfma_f32_16x16x32_bf16 v[60:63], v[148:151], v[178:181], v[60:63]
	v_mfma_f32_16x16x32_bf16 v[56:59], v[152:155], v[174:177], v[56:59]
	v_mfma_f32_16x16x32_bf16 v[56:59], v[156:159], v[178:181], v[56:59]
	v_mfma_f32_16x16x32_bf16 v[52:55], v[144:147], v[182:185], v[52:55]
	v_mfma_f32_16x16x32_bf16 v[52:55], v[148:151], v[186:189], v[52:55]
	v_mfma_f32_16x16x32_bf16 v[48:51], v[152:155], v[182:185], v[48:51]
	v_mfma_f32_16x16x32_bf16 v[48:51], v[156:159], v[186:189], v[48:51]
	v_mfma_f32_16x16x32_bf16 v[44:47], v[144:147], v[190:193], v[44:47]
	v_mfma_f32_16x16x32_bf16 v[44:47], v[148:151], v[194:197], v[44:47]
	v_mfma_f32_16x16x32_bf16 v[40:43], v[152:155], v[190:193], v[40:43]
	v_mfma_f32_16x16x32_bf16 v[40:43], v[156:159], v[194:197], v[40:43]
	v_mfma_f32_16x16x32_bf16 v[36:39], v[144:147], v[198:201], v[36:39]
	v_mfma_f32_16x16x32_bf16 v[36:39], v[148:151], v[206:209], v[36:39]
	v_mfma_f32_16x16x32_bf16 v[32:35], v[152:155], v[198:201], v[32:35]
	v_mfma_f32_16x16x32_bf16 v[32:35], v[156:159], v[206:209], v[32:35]
	s_barrier
; #define PG8_STAGE(bufoff, gbase, voff) do { _Pragma("unroll") for (int _i = 0; _i < 2; ++_i) \
;         __builtin_amdgcn_global_load_lds((const GAS unsigned*)((const GAS char*)(gbase) + (voff)[_i]), (PG8_LAS unsigned*)(lds + (bufoff) + ldsw + _i * 8192), 16, 0, 0); } while (0)
; #define PG8_LDA(dst, b, h) do { _Pragma("unroll") for (int m = 0; m < 4; ++m) _Pragma("unroll") for (int k = 0; k < 2; ++k) dst[m][k] = *(const PG8_LAS bf16x8*)(lds + PG8_SA(b, h) + aoff + m * 2048 + k * 1024); } while (0)
; #define PG8_MMA(ai, bj, At, Bt) do { __builtin_amdgcn_s_setprio(1); _Pragma("unroll") for (int m = 0; m < 4; ++m) _Pragma("unroll") for (int n = 0; n < 2; ++n) _Pragma("unroll") for (int k = 0; k < 2; ++k) \
;         acc[ai][bj][m][n] = __builtin_amdgcn_mfma_f32_16x16x32_bf16(Bt[n][k], At[m][k], acc[ai][bj][m][n], 0, 0, 0); __builtin_amdgcn_s_setprio(0); } while (0)
; #define PG8_WAIT_V(n) asm volatile("s_waitcnt vmcnt(" #n ")" ::: "memory")
; #define PG8_WAIT_L(n) asm volatile("s_waitcnt lgkmcnt(" #n ")" ::: "memory")
; #define PG8_BAR __builtin_amdgcn_s_barrier()
; #define PG8_SCHED __builtin_amdgcn_sched_barrier(0)
; #define PG8_STAGE(bufoff, gbase, voff) do { _Pragma("unroll") for (int _i = 0; _i < 2; ++_i) \
;         __builtin_amdgcn_global_load_lds((const GAS unsigned*)((const GAS char*)(gbase) + (voff)[_i]), (PG8_LAS unsigned*)(lds + (bufoff) + ldsw + _i * 8192), 16, 0, 0); } while (0)
; #define PG8_LDA(dst, b, h) do { _Pragma("unroll") for (int m = 0; m < 4; ++m) _Pragma("unroll") for (int k = 0; k < 2; ++k) dst[m][k] = *(const PG8_LAS bf16x8*)(lds + PG8_SA(b, h) + aoff + m * 2048 + k * 1024); } while (0)
; #define PG8_WAIT_V(n) asm volatile("s_waitcnt vmcnt(" #n ")" ::: "memory")
; #define PG8_BAR __builtin_amdgcn_s_barrier()
; template <class Epi, class Sched, bool ALIGN_EPI = false, bool SP2 = false>
; __device__ __forceinline__ void gemm_phase(PG8_LAS unsigned char* lds, PG8_LAS unsigned char* pf, const Gemm g, const Sched& S, const Epi& E, int wv) {
;     ...
;             PG8_WAIT_V(8); PG8_WAIT_L(0); PG8_BAR; PG8_MMA(0, 0, At, B0); PG8_MMA(0, 1, At, B1); PG8_BAR; PG8_SCHED;
;             PG8_LDA(At, 1, 1); PG8_STAGE(PG8_SB(1, 0), b3, voffB); PG8_STAGE(PG8_SB(1, 1), b3 + hstepB, voffB); PG8_STAGE(PG8_SA(1, 0), a3, voffA);
;             PG8_WAIT_V(8); PG8_WAIT_L(0); PG8_BAR; PG8_MMA(1, 0, At, B0); PG8_MMA(1, 1, At, B1); PG8_BAR; PG8_SCHED;
	s_add_i32 s22, s24, s81
	v_lshl_add_u64 v[214:215], v[214:215], 0, s[16:17]
	s_mov_b32 m0, s22
	ds_read_b128 v[174:177], v205 offset:49152
	ds_read_b128 v[178:181], v205 offset:50176
	ds_read_b128 v[182:185], v205 offset:51200
	ds_read_b128 v[186:189], v205 offset:52224
	ds_read_b128 v[190:193], v205 offset:53248
	ds_read_b128 v[194:197], v205 offset:54272
	ds_read_b128 v[198:201], v205 offset:55296
	ds_read_b128 v[206:209], v205 offset:56320
	global_load_lds_dwordx4 v[214:215], off
	s_add_i32 m0, s22, 0x2000
	s_add_u32 s22, s36, 0x20080
	v_lshl_add_u64 v[214:215], v[216:217], 0, s[16:17]
	s_addc_u32 s23, s37, 0
	s_add_i32 s24, s25, s81
	global_load_lds_dwordx4 v[214:215], off
	v_lshl_add_u64 v[214:215], s[22:23], 0, v[164:165]
	s_mov_b32 m0, s24
	s_nop 0
	global_load_lds_dwordx4 v[214:215], off
	v_lshl_add_u64 v[214:215], s[22:23], 0, v[168:169]
	s_add_i32 m0, s24, 0x2000
	s_nop 0
	global_load_lds_dwordx4 v[214:215], off
	v_lshl_add_u64 v[214:215], v[218:219], 0, s[16:17]
	s_mov_b32 m0, s55
	s_nop 0
	global_load_lds_dwordx4 v[214:215], off
	v_lshl_add_u64 v[214:215], v[220:221], 0, s[16:17]
	s_mov_b32 m0, s56
	s_nop 0
	global_load_lds_dwordx4 v[214:215], off
	s_waitcnt vmcnt(8)
	s_waitcnt lgkmcnt(0)
	s_barrier
	s_waitcnt lgkmcnt(0)
	v_mfma_f32_16x16x32_bf16 v[92:95], v[120:123], v[174:177], v[92:95]
	v_mfma_f32_16x16x32_bf16 v[92:95], v[124:127], v[178:181], v[92:95]
	v_mfma_f32_16x16x32_bf16 v[88:91], v[136:139], v[174:177], v[88:91]
	v_mfma_f32_16x16x32_bf16 v[88:91], v[140:143], v[178:181], v[88:91]
	v_mfma_f32_16x16x32_bf16 v[84:87], v[120:123], v[182:185], v[84:87]
	v_mfma_f32_16x16x32_bf16 v[84:87], v[124:127], v[186:189], v[84:87]
	v_mfma_f32_16x16x32_bf16 v[80:83], v[136:139], v[182:185], v[80:83]
	v_mfma_f32_16x16x32_bf16 v[80:83], v[140:143], v[186:189], v[80:83]
	v_mfma_f32_16x16x32_bf16 v[76:79], v[120:123], v[190:193], v[76:79]
	v_mfma_f32_16x16x32_bf16 v[76:79], v[124:127], v[194:197], v[76:79]
	v_mfma_f32_16x16x32_bf16 v[72:75], v[136:139], v[190:193], v[72:75]
	v_mfma_f32_16x16x32_bf16 v[72:75], v[140:143], v[194:197], v[72:75]
	v_mfma_f32_16x16x32_bf16 v[68:71], v[120:123], v[198:201], v[68:71]
	v_mfma_f32_16x16x32_bf16 v[68:71], v[124:127], v[206:209], v[68:71]
	v_mfma_f32_16x16x32_bf16 v[64:67], v[136:139], v[198:201], v[64:67]
	v_mfma_f32_16x16x32_bf16 v[64:67], v[140:143], v[206:209], v[64:67]
	v_mfma_f32_16x16x32_bf16 v[28:31], v[144:147], v[174:177], v[28:31]
	v_mfma_f32_16x16x32_bf16 v[28:31], v[148:151], v[178:181], v[28:31]
	v_mfma_f32_16x16x32_bf16 v[24:27], v[152:155], v[174:177], v[24:27]
	v_mfma_f32_16x16x32_bf16 v[24:27], v[156:159], v[178:181], v[24:27]
	v_mfma_f32_16x16x32_bf16 v[20:23], v[144:147], v[182:185], v[20:23]
	v_mfma_f32_16x16x32_bf16 v[20:23], v[148:151], v[186:189], v[20:23]
	v_mfma_f32_16x16x32_bf16 v[16:19], v[152:155], v[182:185], v[16:19]
	v_mfma_f32_16x16x32_bf16 v[16:19], v[156:159], v[186:189], v[16:19]
	v_mfma_f32_16x16x32_bf16 v[12:15], v[144:147], v[190:193], v[12:15]
	v_mfma_f32_16x16x32_bf16 v[12:15], v[148:151], v[194:197], v[12:15]
	v_mfma_f32_16x16x32_bf16 v[8:11], v[152:155], v[190:193], v[8:11]
	v_mfma_f32_16x16x32_bf16 v[8:11], v[156:159], v[194:197], v[8:11]
	v_mfma_f32_16x16x32_bf16 v[4:7], v[144:147], v[198:201], v[4:7]
	v_mfma_f32_16x16x32_bf16 v[4:7], v[148:151], v[206:209], v[4:7]
	v_mfma_f32_16x16x32_bf16 v[0:3], v[152:155], v[198:201], v[0:3]
	v_mfma_f32_16x16x32_bf16 v[0:3], v[156:159], v[206:209], v[0:3]
	s_barrier
	s_add_i32 s21, s21, 2
	s_add_u32 s13, s13, 0x100
	s_addc_u32 s20, s20, 0
	s_add_u32 s14, s14, 0x100
	s_addc_u32 s15, s15, 0
	s_cmp_gt_u32 s21, 5

; #define PG8_STAGE(bufoff, gbase, voff) do { _Pragma("unroll") for (int _i = 0; _i < 2; ++_i) \
;         __builtin_amdgcn_global_load_lds((const GAS unsigned*)((const GAS char*)(gbase) + (voff)[_i]), (PG8_LAS unsigned*)(lds + (bufoff) + ldsw + _i * 8192), 16, 0, 0); } while (0)
; #define PG8_LDA(dst, b, h) do { _Pragma("unroll") for (int m = 0; m < 4; ++m) _Pragma("unroll") for (int k = 0; k < 2; ++k) dst[m][k] = *(const PG8_LAS bf16x8*)(lds + PG8_SA(b, h) + aoff + m * 2048 + k * 1024); } while (0)
; #define PG8_LDB(dst, b, h) do { _Pragma("unroll") for (int n = 0; n < 2; ++n) _Pragma("unroll") for (int k = 0; k < 2; ++k) dst[n][k] = *(const PG8_LAS bf16x8*)(lds + PG8_SB(b, h) + boff + n * 2048 + k * 1024); } while (0)
; #define PG8_MMA(ai, bj, At, Bt) do { __builtin_amdgcn_s_setprio(1); _Pragma("unroll") for (int m = 0; m < 4; ++m) _Pragma("unroll") for (int n = 0; n < 2; ++n) _Pragma("unroll") for (int k = 0; k < 2; ++k) \
;         acc[ai][bj][m][n] = __builtin_amdgcn_mfma_f32_16x16x32_bf16(Bt[n][k], At[m][k], acc[ai][bj][m][n], 0, 0, 0); __builtin_amdgcn_s_setprio(0); } while (0)
; #define PG8_WAIT_V(n) asm volatile("s_waitcnt vmcnt(" #n ")" ::: "memory")
; #define PG8_WAIT_L(n) asm volatile("s_waitcnt lgkmcnt(" #n ")" ::: "memory")
; #define PG8_BAR __builtin_amdgcn_s_barrier()
; #define PG8_SCHED __builtin_amdgcn_sched_barrier(0)
; #define PG8_WAIT_V(n) asm volatile("s_waitcnt vmcnt(" #n ")" ::: "memory")
; template <class Epi, class Sched, bool ALIGN_EPI = false, bool SP2 = false>
; __device__ __forceinline__ void gemm_phase(PG8_LAS unsigned char* lds, PG8_LAS unsigned char* pf, const Gemm g, const Sched& S, const Epi& E, int wv) {
;     ...
;             PG8_LDB(B0, 0, 0); PG8_LDB(B1, 0, 1); PG8_SCHED; PG8_LDA(At, 0, 0); PG8_STAGE(PG8_SA(1, 1), a1 + (Sched::SPLIT ? hsA : (long)hstepA), voffA);
;             PG8_WAIT_V(8); PG8_WAIT_L(0); PG8_BAR; PG8_MMA(0, 0, At, B0); PG8_MMA(0, 1, At, B1); PG8_BAR; PG8_SCHED;
;             PG8_LDA(At, 0, 1); PG8_STAGE(PG8_SB(0, 0), b2, voffB); PG8_STAGE(PG8_SB(0, 1), b2 + hstepB, voffB); PG8_STAGE(PG8_SA(0, 0), a2, voffA);
;     ...
;         for (int a = 0; a < 2; ++a)
; #pragma unroll
;             for (int b = 0; b < 2; ++b)
; #pragma unroll
;                 for (int m = 0; m < 4; ++m)
; #pragma unroll
;                     for (int n = 0; n < 2; ++n) acc[a][b][m][n] = (f32x4){0.f, 0.f, 0.f, 0.f};
.LBB0_1413:
	s_ashr_i32 s9, s8, 31
	s_lshl_b64 s[14:15], s[8:9], 20
	s_add_u32 s14, s69, s14
	s_addc_u32 s15, s72, s15
	s_and_b64 s[22:23], s[36:37], exec
	s_cselect_b32 s9, s15, s43
	s_cselect_b32 s11, s14, s42
	s_add_u32 s22, s42, 0x100
	s_addc_u32 s23, s43, 0
	s_add_u32 s36, s40, 0x80080
	s_addc_u32 s37, s41, 0
	s_mov_b32 s24, -2
.Lpeel_fu:
	s_add_u32 s25, s36, 0xfff80080
	s_addc_u32 s28, s37, -1
	s_add_i32 s42, 0, 0x10000
	s_cmp_eq_u32 s24, 28
	s_cselect_b32 s29, s13, s28
	s_cselect_b32 s28, s12, s25
	s_cselect_b32 s41, s9, s23
	s_cselect_b32 s40, s11, s22
	s_add_i32 s25, 0, 0x14000
	v_add_u32_e32 v132, s42, v159
	v_add_u32_e32 v160, s25, v159
	ds_read_b128 v[120:123], v132
	ds_read_b128 v[124:127], v132 offset:1024
	ds_read_b128 v[128:131], v132 offset:2048
	ds_read_b128 v[132:135], v132 offset:3072
	ds_read_b128 v[164:167], v160
	ds_read_b128 v[168:171], v160 offset:1024
	ds_read_b128 v[172:175], v160 offset:2048
	ds_read_b128 v[176:179], v160 offset:3072
	v_lshl_add_u64 v[208:209], s[36:37], 0, v[154:155]
	s_add_i32 m0, s1, 0xc000
	ds_read_b128 v[180:183], v162
	ds_read_b128 v[184:187], v162 offset:1024
	ds_read_b128 v[188:191], v162 offset:2048
	ds_read_b128 v[192:195], v162 offset:3072
	ds_read_b128 v[196:199], v162 offset:4096
	ds_read_b128 v[200:203], v162 offset:5120
	ds_read_b128 v[204:207], v162 offset:6144
	ds_read_b128 v[214:217], v162 offset:7168
	global_load_lds_dwordx4 v[208:209], off
	v_lshl_add_u64 v[208:209], s[36:37], 0, v[152:153]
	s_add_i32 m0, s1, 0xe000
	s_nop 0
	global_load_lds_dwordx4 v[208:209], off
	s_waitcnt vmcnt(8)
	s_waitcnt lgkmcnt(0)
	s_barrier
	s_waitcnt lgkmcnt(0)
	v_mfma_f32_16x16x32_bf16 v[140:143], v[120:123], v[180:183], 0
	v_mfma_f32_16x16x32_bf16 v[140:143], v[124:127], v[184:187], v[140:143]
	v_mfma_f32_16x16x32_bf16 v[136:139], v[128:131], v[180:183], 0
	v_mfma_f32_16x16x32_bf16 v[136:139], v[132:135], v[184:187], v[136:139]
	v_mfma_f32_16x16x32_bf16 v[108:111], v[120:123], v[188:191], 0
	v_mfma_f32_16x16x32_bf16 v[108:111], v[124:127], v[192:195], v[108:111]
	v_mfma_f32_16x16x32_bf16 v[104:107], v[128:131], v[188:191], 0
	v_mfma_f32_16x16x32_bf16 v[104:107], v[132:135], v[192:195], v[104:107]
	v_mfma_f32_16x16x32_bf16 v[92:95], v[120:123], v[196:199], 0
	v_mfma_f32_16x16x32_bf16 v[92:95], v[124:127], v[200:203], v[92:95]
	v_mfma_f32_16x16x32_bf16 v[88:91], v[128:131], v[196:199], 0
	v_mfma_f32_16x16x32_bf16 v[88:91], v[132:135], v[200:203], v[88:91]
	v_mfma_f32_16x16x32_bf16 v[76:79], v[120:123], v[204:207], 0
	v_mfma_f32_16x16x32_bf16 v[76:79], v[124:127], v[214:217], v[76:79]
	v_mfma_f32_16x16x32_bf16 v[72:75], v[128:131], v[204:207], 0
	v_mfma_f32_16x16x32_bf16 v[72:75], v[132:135], v[214:217], v[72:75]
	v_mfma_f32_16x16x32_bf16 v[116:119], v[164:167], v[180:183], 0
	v_mfma_f32_16x16x32_bf16 v[116:119], v[168:171], v[184:187], v[116:119]
	v_mfma_f32_16x16x32_bf16 v[112:115], v[172:175], v[180:183], 0
	v_mfma_f32_16x16x32_bf16 v[112:115], v[176:179], v[184:187], v[112:115]
	v_mfma_f32_16x16x32_bf16 v[100:103], v[164:167], v[188:191], 0
	v_mfma_f32_16x16x32_bf16 v[100:103], v[168:171], v[192:195], v[100:103]
	v_mfma_f32_16x16x32_bf16 v[96:99], v[172:175], v[188:191], 0
	v_mfma_f32_16x16x32_bf16 v[96:99], v[176:179], v[192:195], v[96:99]
	v_mfma_f32_16x16x32_bf16 v[84:87], v[164:167], v[196:199], 0
	v_mfma_f32_16x16x32_bf16 v[84:87], v[168:171], v[200:203], v[84:87]
	v_mfma_f32_16x16x32_bf16 v[80:83], v[172:175], v[196:199], 0
	v_mfma_f32_16x16x32_bf16 v[80:83], v[176:179], v[200:203], v[80:83]
	v_mfma_f32_16x16x32_bf16 v[68:71], v[164:167], v[204:207], 0
	v_mfma_f32_16x16x32_bf16 v[68:71], v[168:171], v[214:217], v[68:71]
	v_mfma_f32_16x16x32_bf16 v[64:67], v[172:175], v[204:207], 0
	v_mfma_f32_16x16x32_bf16 v[64:67], v[176:179], v[214:217], v[64:67]
	s_barrier
	s_add_i32 s42, s42, s27
	v_lshl_add_u64 v[208:209], s[40:41], 0, v[146:147]
	s_mov_b32 m0, s42
	ds_read_b128 v[180:183], v162 offset:16384
	ds_read_b128 v[184:187], v162 offset:17408
	ds_read_b128 v[188:191], v162 offset:18432
	ds_read_b128 v[192:195], v162 offset:19456
	ds_read_b128 v[196:199], v162 offset:20480
	ds_read_b128 v[200:203], v162 offset:21504
	ds_read_b128 v[204:207], v162 offset:22528
	ds_read_b128 v[214:217], v162 offset:23552
	global_load_lds_dwordx4 v[208:209], off
	s_add_i32 m0, s42, 0x2000
	s_add_u32 s42, s40, 0x80000
	v_lshl_add_u64 v[218:219], s[40:41], 0, v[150:151]
	s_addc_u32 s43, s41, 0
	s_add_i32 s25, s25, s27
	global_load_lds_dwordx4 v[218:219], off
	v_lshl_add_u64 v[220:221], s[42:43], 0, v[146:147]
	s_mov_b32 m0, s25
	v_lshl_add_u64 v[222:223], s[28:29], 0, v[148:149]
	global_load_lds_dwordx4 v[220:221], off
	v_lshl_add_u64 v[220:221], s[42:43], 0, v[150:151]
	s_add_i32 m0, s25, 0x2000
	s_nop 0
	global_load_lds_dwordx4 v[220:221], off
	v_lshl_add_u64 v[220:221], s[28:29], 0, v[144:145]
	s_mov_b32 m0, s1
	s_nop 0
	global_load_lds_dwordx4 v[220:221], off
	s_mov_b32 m0, s39
	s_nop 0
	global_load_lds_dwordx4 v[222:223], off
	s_waitcnt vmcnt(8)
	s_waitcnt lgkmcnt(0)
	s_barrier
; #define PG8_STAGE(bufoff, gbase, voff) do { _Pragma("unroll") for (int _i = 0; _i < 2; ++_i) \
;         __builtin_amdgcn_global_load_lds((const GAS unsigned*)((const GAS char*)(gbase) + (voff)[_i]), (PG8_LAS unsigned*)(lds + (bufoff) + ldsw + _i * 8192), 16, 0, 0); } while (0)
; #define PG8_LDA(dst, b, h) do { _Pragma("unroll") for (int m = 0; m < 4; ++m) _Pragma("unroll") for (int k = 0; k < 2; ++k) dst[m][k] = *(const PG8_LAS bf16x8*)(lds + PG8_SA(b, h) + aoff + m * 2048 + k * 1024); } while (0)
; #define PG8_LDB(dst, b, h) do { _Pragma("unroll") for (int n = 0; n < 2; ++n) _Pragma("unroll") for (int k = 0; k < 2; ++k) dst[n][k] = *(const PG8_LAS bf16x8*)(lds + PG8_SB(b, h) + boff + n * 2048 + k * 1024); } while (0)
; #define PG8_MMA(ai, bj, At, Bt) do { __builtin_amdgcn_s_setprio(1); _Pragma("unroll") for (int m = 0; m < 4; ++m) _Pragma("unroll") for (int n = 0; n < 2; ++n) _Pragma("unroll") for (int k = 0; k < 2; ++k) \
;         acc[ai][bj][m][n] = __builtin_amdgcn_mfma_f32_16x16x32_bf16(Bt[n][k], At[m][k], acc[ai][bj][m][n], 0, 0, 0); __builtin_amdgcn_s_setprio(0); } while (0)
; #define PG8_WAIT_V(n) asm volatile("s_waitcnt vmcnt(" #n ")" ::: "memory")
; #define PG8_WAIT_L(n) asm volatile("s_waitcnt lgkmcnt(" #n ")" ::: "memory")
; #define PG8_BAR __builtin_amdgcn_s_barrier()
; #define PG8_SCHED __builtin_amdgcn_sched_barrier(0)
; #define PG8_STAGE(bufoff, gbase, voff) do { _Pragma("unroll") for (int _i = 0; _i < 2; ++_i) \
;         __builtin_amdgcn_global_load_lds((const GAS unsigned*)((const GAS char*)(gbase) + (voff)[_i]), (PG8_LAS unsigned*)(lds + (bufoff) + ldsw + _i * 8192), 16, 0, 0); } while (0)
; #define PG8_BAR __builtin_amdgcn_s_barrier()
; template <class Epi, class Sched, bool ALIGN_EPI = false, bool SP2 = false>
; __device__ __forceinline__ void gemm_phase(PG8_LAS unsigned char* lds, PG8_LAS unsigned char* pf, const Gemm g, const Sched& S, const Epi& E, int wv) {
;     ...
;             PG8_WAIT_V(8); PG8_WAIT_L(0); PG8_BAR; PG8_MMA(1, 0, At, B0); PG8_MMA(1, 1, At, B1); PG8_BAR; PG8_SCHED;
;             PG8_LDB(B0, 1, 0); PG8_LDB(B1, 1, 1); PG8_SCHED; PG8_LDA(At, 1, 0); PG8_STAGE(PG8_SA(0, 1), a2 + (Sched::SPLIT ? ((last && has_next) ? (nxt.kh > 0 ? -(long)hstepA : (long)hstepA) : hsA) : (long)hstepA), voffA);
;             PG8_WAIT_V(8); PG8_WAIT_L(0); PG8_BAR; PG8_MMA(0, 0, At, B0); PG8_MMA(0, 1, At, B1); PG8_BAR; PG8_SCHED;
	s_waitcnt lgkmcnt(0)
	v_mfma_f32_16x16x32_bf16 v[60:63], v[120:123], v[180:183], 0
	v_mfma_f32_16x16x32_bf16 v[60:63], v[124:127], v[184:187], v[60:63]
	v_mfma_f32_16x16x32_bf16 v[56:59], v[128:131], v[180:183], 0
	v_mfma_f32_16x16x32_bf16 v[56:59], v[132:135], v[184:187], v[56:59]
	v_mfma_f32_16x16x32_bf16 v[44:47], v[120:123], v[188:191], 0
	v_mfma_f32_16x16x32_bf16 v[44:47], v[124:127], v[192:195], v[44:47]
	v_mfma_f32_16x16x32_bf16 v[40:43], v[128:131], v[188:191], 0
	v_mfma_f32_16x16x32_bf16 v[40:43], v[132:135], v[192:195], v[40:43]
	v_mfma_f32_16x16x32_bf16 v[28:31], v[120:123], v[196:199], 0
	v_mfma_f32_16x16x32_bf16 v[28:31], v[124:127], v[200:203], v[28:31]
	v_mfma_f32_16x16x32_bf16 v[24:27], v[128:131], v[196:199], 0
	v_mfma_f32_16x16x32_bf16 v[24:27], v[132:135], v[200:203], v[24:27]
	v_mfma_f32_16x16x32_bf16 v[12:15], v[120:123], v[204:207], 0
	v_mfma_f32_16x16x32_bf16 v[12:15], v[124:127], v[214:217], v[12:15]
	v_mfma_f32_16x16x32_bf16 v[8:11], v[128:131], v[204:207], 0
	v_mfma_f32_16x16x32_bf16 v[8:11], v[132:135], v[214:217], v[8:11]
	v_mfma_f32_16x16x32_bf16 v[52:55], v[164:167], v[180:183], 0
	v_mfma_f32_16x16x32_bf16 v[52:55], v[168:171], v[184:187], v[52:55]
	v_mfma_f32_16x16x32_bf16 v[48:51], v[172:175], v[180:183], 0
	v_mfma_f32_16x16x32_bf16 v[48:51], v[176:179], v[184:187], v[48:51]
	v_mfma_f32_16x16x32_bf16 v[36:39], v[164:167], v[188:191], 0
	v_mfma_f32_16x16x32_bf16 v[36:39], v[168:171], v[192:195], v[36:39]
	v_mfma_f32_16x16x32_bf16 v[32:35], v[172:175], v[188:191], 0
	v_mfma_f32_16x16x32_bf16 v[32:35], v[176:179], v[192:195], v[32:35]
	v_mfma_f32_16x16x32_bf16 v[20:23], v[164:167], v[196:199], 0
	v_mfma_f32_16x16x32_bf16 v[20:23], v[168:171], v[200:203], v[20:23]
	v_mfma_f32_16x16x32_bf16 v[16:19], v[172:175], v[196:199], 0
	v_mfma_f32_16x16x32_bf16 v[16:19], v[176:179], v[200:203], v[16:19]
	v_mfma_f32_16x16x32_bf16 v[4:7], v[164:167], v[204:207], 0
	v_mfma_f32_16x16x32_bf16 v[4:7], v[168:171], v[214:217], v[4:7]
	v_mfma_f32_16x16x32_bf16 v[0:3], v[172:175], v[204:207], 0
	v_mfma_f32_16x16x32_bf16 v[0:3], v[176:179], v[214:217], v[0:3]
	s_barrier
	s_add_i32 s25, 0, 0x18000
	s_add_i32 s42, 0, 0x1c000
	v_add_u32_e32 v132, s25, v159
	v_add_u32_e32 v160, s42, v159
	ds_read_b128 v[120:123], v132
	ds_read_b128 v[124:127], v132 offset:1024
	ds_read_b128 v[128:131], v132 offset:2048
	ds_read_b128 v[132:135], v132 offset:3072
	ds_read_b128 v[164:167], v160
	ds_read_b128 v[168:171], v160 offset:1024
	ds_read_b128 v[172:175], v160 offset:2048
	ds_read_b128 v[176:179], v160 offset:3072
	s_add_u32 s28, s28, 0x80000
	s_addc_u32 s29, s29, 0
	s_mov_b32 m0, s44
	v_lshl_add_u64 v[224:225], s[28:29], 0, v[144:145]
	ds_read_b128 v[180:183], v162 offset:32768
	ds_read_b128 v[184:187], v162 offset:33792
	ds_read_b128 v[188:191], v162 offset:34816
	ds_read_b128 v[192:195], v162 offset:35840
	ds_read_b128 v[196:199], v162 offset:36864
	ds_read_b128 v[200:203], v162 offset:37888
	ds_read_b128 v[204:207], v162 offset:38912
	ds_read_b128 v[214:217], v162 offset:39936
	global_load_lds_dwordx4 v[224:225], off
	v_lshl_add_u64 v[224:225], s[28:29], 0, v[148:149]
	s_mov_b32 m0, s45
	s_nop 0
	global_load_lds_dwordx4 v[224:225], off
	s_waitcnt vmcnt(8)
	s_waitcnt lgkmcnt(0)
	s_barrier
	s_waitcnt lgkmcnt(0)
	v_mfma_f32_16x16x32_bf16 v[140:143], v[120:123], v[180:183], v[140:143]
	v_mfma_f32_16x16x32_bf16 v[140:143], v[124:127], v[184:187], v[140:143]
	v_mfma_f32_16x16x32_bf16 v[136:139], v[128:131], v[180:183], v[136:139]
	v_mfma_f32_16x16x32_bf16 v[136:139], v[132:135], v[184:187], v[136:139]
	v_mfma_f32_16x16x32_bf16 v[108:111], v[120:123], v[188:191], v[108:111]
	v_mfma_f32_16x16x32_bf16 v[108:111], v[124:127], v[192:195], v[108:111]
	v_mfma_f32_16x16x32_bf16 v[104:107], v[128:131], v[188:191], v[104:107]
	v_mfma_f32_16x16x32_bf16 v[104:107], v[132:135], v[192:195], v[104:107]
	v_mfma_f32_16x16x32_bf16 v[92:95], v[120:123], v[196:199], v[92:95]
	v_mfma_f32_16x16x32_bf16 v[92:95], v[124:127], v[200:203], v[92:95]
	v_mfma_f32_16x16x32_bf16 v[88:91], v[128:131], v[196:199], v[88:91]
	v_mfma_f32_16x16x32_bf16 v[88:91], v[132:135], v[200:203], v[88:91]
	v_mfma_f32_16x16x32_bf16 v[76:79], v[120:123], v[204:207], v[76:79]
	v_mfma_f32_16x16x32_bf16 v[76:79], v[124:127], v[214:217], v[76:79]
	v_mfma_f32_16x16x32_bf16 v[72:75], v[128:131], v[204:207], v[72:75]
	v_mfma_f32_16x16x32_bf16 v[72:75], v[132:135], v[214:217], v[72:75]
	v_mfma_f32_16x16x32_bf16 v[116:119], v[164:167], v[180:183], v[116:119]
	v_mfma_f32_16x16x32_bf16 v[116:119], v[168:171], v[184:187], v[116:119]
	v_mfma_f32_16x16x32_bf16 v[112:115], v[172:175], v[180:183], v[112:115]
	v_mfma_f32_16x16x32_bf16 v[112:115], v[176:179], v[184:187], v[112:115]
	v_mfma_f32_16x16x32_bf16 v[100:103], v[164:167], v[188:191], v[100:103]
	v_mfma_f32_16x16x32_bf16 v[100:103], v[168:171], v[192:195], v[100:103]
	v_mfma_f32_16x16x32_bf16 v[96:99], v[172:175], v[188:191], v[96:99]
	v_mfma_f32_16x16x32_bf16 v[96:99], v[176:179], v[192:195], v[96:99]
	v_mfma_f32_16x16x32_bf16 v[84:87], v[164:167], v[196:199], v[84:87]
	v_mfma_f32_16x16x32_bf16 v[84:87], v[168:171], v[200:203], v[84:87]
	v_mfma_f32_16x16x32_bf16 v[80:83], v[172:175], v[196:199], v[80:83]
	v_mfma_f32_16x16x32_bf16 v[80:83], v[176:179], v[200:203], v[80:83]
	v_mfma_f32_16x16x32_bf16 v[68:71], v[164:167], v[204:207], v[68:71]
	v_mfma_f32_16x16x32_bf16 v[68:71], v[168:171], v[214:217], v[68:71]
	v_mfma_f32_16x16x32_bf16 v[64:67], v[172:175], v[204:207], v[64:67]
	v_mfma_f32_16x16x32_bf16 v[64:67], v[176:179], v[214:217], v[64:67]
	s_barrier
; #define GAS __attribute__((address_space(1)))
; #define PG8_STAGE(bufoff, gbase, voff) do { _Pragma("unroll") for (int _i = 0; _i < 2; ++_i) \
;         __builtin_amdgcn_global_load_lds((const GAS unsigned*)((const GAS char*)(gbase) + (voff)[_i]), (PG8_LAS unsigned*)(lds + (bufoff) + ldsw + _i * 8192), 16, 0, 0); } while (0)
; #define PG8_LDA(dst, b, h) do { _Pragma("unroll") for (int m = 0; m < 4; ++m) _Pragma("unroll") for (int k = 0; k < 2; ++k) dst[m][k] = *(const PG8_LAS bf16x8*)(lds + PG8_SA(b, h) + aoff + m * 2048 + k * 1024); } while (0)
; #define PG8_MMA(ai, bj, At, Bt) do { __builtin_amdgcn_s_setprio(1); _Pragma("unroll") for (int m = 0; m < 4; ++m) _Pragma("unroll") for (int n = 0; n < 2; ++n) _Pragma("unroll") for (int k = 0; k < 2; ++k) \
;         acc[ai][bj][m][n] = __builtin_amdgcn_mfma_f32_16x16x32_bf16(Bt[n][k], At[m][k], acc[ai][bj][m][n], 0, 0, 0); __builtin_amdgcn_s_setprio(0); } while (0)
; #define PG8_WAIT_V(n) asm volatile("s_waitcnt vmcnt(" #n ")" ::: "memory")
; #define PG8_WAIT_L(n) asm volatile("s_waitcnt lgkmcnt(" #n ")" ::: "memory")
; #define PG8_BAR __builtin_amdgcn_s_barrier()
; #define PG8_SCHED __builtin_amdgcn_sched_barrier(0)
; #define PG8_STAGE(bufoff, gbase, voff) do { _Pragma("unroll") for (int _i = 0; _i < 2; ++_i) \
;         __builtin_amdgcn_global_load_lds((const GAS unsigned*)((const GAS char*)(gbase) + (voff)[_i]), (PG8_LAS unsigned*)(lds + (bufoff) + ldsw + _i * 8192), 16, 0, 0); } while (0)
; #define PG8_WAIT_V(n) asm volatile("s_waitcnt vmcnt(" #n ")" ::: "memory")
; #define PG8_BAR __builtin_amdgcn_s_barrier()
; template <class Epi, class Sched, bool ALIGN_EPI = false, bool SP2 = false>
; __device__ __forceinline__ void gemm_phase(PG8_LAS unsigned char* lds, PG8_LAS unsigned char* pf, const Gemm g, const Sched& S, const Epi& E, int wv) {
;     ...
;         for (int t = 0; t < ntu; t += 2) {
;             const bool last = (t == ntu - 2);
;             const GAS char* a1 = cA + (size_t)(t + 1) * kstep;
;             const GAS char* a2 = last ? nA : cA + (size_t)(t + 2) * kstep; const GAS char* b2 = last ? nB : cB + (size_t)(t + 2) * kstep;
;     ...
;             PG8_LDA(At, 1, 1); PG8_STAGE(PG8_SB(1, 0), b3, voffB); PG8_STAGE(PG8_SB(1, 1), b3 + hstepB, voffB); PG8_STAGE(PG8_SA(1, 0), a3, voffA);
;             PG8_WAIT_V(8); PG8_WAIT_L(0); PG8_BAR; PG8_MMA(1, 0, At, B0); PG8_MMA(1, 1, At, B1); PG8_BAR; PG8_SCHED;
	s_add_i32 s25, s25, s27
	v_lshl_add_u64 v[208:209], v[208:209], 0, s[16:17]
	s_mov_b32 m0, s25
	ds_read_b128 v[180:183], v162 offset:49152
	ds_read_b128 v[184:187], v162 offset:50176
	ds_read_b128 v[188:191], v162 offset:51200
	ds_read_b128 v[192:195], v162 offset:52224
	ds_read_b128 v[196:199], v162 offset:53248
	ds_read_b128 v[200:203], v162 offset:54272
	ds_read_b128 v[204:207], v162 offset:55296
	ds_read_b128 v[214:217], v162 offset:56320
	global_load_lds_dwordx4 v[208:209], off
	s_add_i32 m0, s25, 0x2000
	s_add_u32 s28, s40, 0x80080
	v_lshl_add_u64 v[208:209], v[218:219], 0, s[16:17]
	s_addc_u32 s29, s41, 0
	s_add_i32 s25, s42, s27
	global_load_lds_dwordx4 v[208:209], off
	v_lshl_add_u64 v[208:209], s[28:29], 0, v[146:147]
	s_mov_b32 m0, s25
	s_nop 0
	global_load_lds_dwordx4 v[208:209], off
	v_lshl_add_u64 v[208:209], s[28:29], 0, v[150:151]
	s_add_i32 m0, s25, 0x2000
	s_nop 0
	global_load_lds_dwordx4 v[208:209], off
	v_lshl_add_u64 v[208:209], v[220:221], 0, s[16:17]
	s_mov_b32 m0, s20
	s_nop 0
	global_load_lds_dwordx4 v[208:209], off
	v_lshl_add_u64 v[208:209], v[222:223], 0, s[16:17]
	s_mov_b32 m0, s21
	s_nop 0
	global_load_lds_dwordx4 v[208:209], off
	s_waitcnt vmcnt(8)
	s_waitcnt lgkmcnt(0)
	s_barrier
	s_waitcnt lgkmcnt(0)
	v_mfma_f32_16x16x32_bf16 v[60:63], v[120:123], v[180:183], v[60:63]
	v_mfma_f32_16x16x32_bf16 v[60:63], v[124:127], v[184:187], v[60:63]
	v_mfma_f32_16x16x32_bf16 v[56:59], v[128:131], v[180:183], v[56:59]
	v_mfma_f32_16x16x32_bf16 v[56:59], v[132:135], v[184:187], v[56:59]
	v_mfma_f32_16x16x32_bf16 v[44:47], v[120:123], v[188:191], v[44:47]
	v_mfma_f32_16x16x32_bf16 v[44:47], v[124:127], v[192:195], v[44:47]
	v_mfma_f32_16x16x32_bf16 v[40:43], v[128:131], v[188:191], v[40:43]
	v_mfma_f32_16x16x32_bf16 v[40:43], v[132:135], v[192:195], v[40:43]
	v_mfma_f32_16x16x32_bf16 v[28:31], v[120:123], v[196:199], v[28:31]
	v_mfma_f32_16x16x32_bf16 v[28:31], v[124:127], v[200:203], v[28:31]
	v_mfma_f32_16x16x32_bf16 v[24:27], v[128:131], v[196:199], v[24:27]
	v_mfma_f32_16x16x32_bf16 v[24:27], v[132:135], v[200:203], v[24:27]
	v_mfma_f32_16x16x32_bf16 v[12:15], v[120:123], v[204:207], v[12:15]
	v_mfma_f32_16x16x32_bf16 v[12:15], v[124:127], v[214:217], v[12:15]
	v_mfma_f32_16x16x32_bf16 v[8:11], v[128:131], v[204:207], v[8:11]
	v_mfma_f32_16x16x32_bf16 v[8:11], v[132:135], v[214:217], v[8:11]
	v_mfma_f32_16x16x32_bf16 v[52:55], v[164:167], v[180:183], v[52:55]
	v_mfma_f32_16x16x32_bf16 v[52:55], v[168:171], v[184:187], v[52:55]
	v_mfma_f32_16x16x32_bf16 v[48:51], v[172:175], v[180:183], v[48:51]
	v_mfma_f32_16x16x32_bf16 v[48:51], v[176:179], v[184:187], v[48:51]
	v_mfma_f32_16x16x32_bf16 v[36:39], v[164:167], v[188:191], v[36:39]
	v_mfma_f32_16x16x32_bf16 v[36:39], v[168:171], v[192:195], v[36:39]
	v_mfma_f32_16x16x32_bf16 v[32:35], v[172:175], v[188:191], v[32:35]
	v_mfma_f32_16x16x32_bf16 v[32:35], v[176:179], v[192:195], v[32:35]
	v_mfma_f32_16x16x32_bf16 v[20:23], v[164:167], v[196:199], v[20:23]
	v_mfma_f32_16x16x32_bf16 v[20:23], v[168:171], v[200:203], v[20:23]
	v_mfma_f32_16x16x32_bf16 v[16:19], v[172:175], v[196:199], v[16:19]
	v_mfma_f32_16x16x32_bf16 v[16:19], v[176:179], v[200:203], v[16:19]
	v_mfma_f32_16x16x32_bf16 v[4:7], v[164:167], v[204:207], v[4:7]
	v_mfma_f32_16x16x32_bf16 v[4:7], v[168:171], v[214:217], v[4:7]
	v_mfma_f32_16x16x32_bf16 v[0:3], v[172:175], v[204:207], v[0:3]
	v_mfma_f32_16x16x32_bf16 v[0:3], v[176:179], v[214:217], v[0:3]
	s_barrier
	s_add_i32 s24, s24, 2
	s_add_u32 s22, s22, 0x100
	s_addc_u32 s23, s23, 0
	s_add_u32 s36, s36, 0x100
	s_addc_u32 s37, s37, 0
	s_cmp_gt_u32 s24, 29

; #define GAS __attribute__((address_space(1)))
; #define PG8_STAGE(bufoff, gbase, voff) do { _Pragma("unroll") for (int _i = 0; _i < 2; ++_i) \
;         __builtin_amdgcn_global_load_lds((const GAS unsigned*)((const GAS char*)(gbase) + (voff)[_i]), (PG8_LAS unsigned*)(lds + (bufoff) + ldsw + _i * 8192), 16, 0, 0); } while (0)
; #define PG8_LDA(dst, b, h) do { _Pragma("unroll") for (int m = 0; m < 4; ++m) _Pragma("unroll") for (int k = 0; k < 2; ++k) dst[m][k] = *(const PG8_LAS bf16x8*)(lds + PG8_SA(b, h) + aoff + m * 2048 + k * 1024); } while (0)
; #define PG8_LDB(dst, b, h) do { _Pragma("unroll") for (int n = 0; n < 2; ++n) _Pragma("unroll") for (int k = 0; k < 2; ++k) dst[n][k] = *(const PG8_LAS bf16x8*)(lds + PG8_SB(b, h) + boff + n * 2048 + k * 1024); } while (0)
; template <class Epi, class Sched, bool ALIGN_EPI = false, bool SP2 = false>
; __device__ __forceinline__ void gemm_phase(PG8_LAS unsigned char* lds, PG8_LAS unsigned char* pf, const Gemm g, const Sched& S, const Epi& E, int wv) {
;     ...
;         const bool has_next = S.next(ui + 1, nxt);
;         const GAS char* nA = has_next ? PG8_ABASE(nxt) : cA; const GAS char* nB = has_next ? PG8_BBASE(nxt) : cB;
;         if constexpr (Sched::SPLIT) { if (has_next && nxt.kh > 0) nA += hstepA; }
;         int ntu = nt; if constexpr (Sched::SPLIT) { if (cur.kh >= 0) ntu = nt >> 1; }
;         for (int t = 0; t < ntu; t += 2) {
;             const bool last = (t == ntu - 2);
;             const GAS char* a1 = cA + (size_t)(t + 1) * kstep;
;             const GAS char* a2 = last ? nA : cA + (size_t)(t + 2) * kstep; const GAS char* b2 = last ? nB : cB + (size_t)(t + 2) * kstep;
;             const GAS char* a3 = a2 + kstep; const GAS char* b3 = b2 + kstep;
;             if (last && has_next) S.a_ready(nxt);
;             if constexpr (SP2) {
;             PG8_LDB(B0, 0, 0); PG8_LDB(B1, 0, 1); PG8_SCHED; PG8_LDA(At, 0, 0); PG8_STAGE(PG8_SA(1, 1), a1 + (Sched::SPLIT ? hsA : (long)hstepA), voffA);
;             PG8_WAIT_V(8); PG8_WAIT_L(0); PG8_BAR; PG8_MMA(0, 0, At, B0); PG8_MMA(0, 1, At, B1); PG8_BAR; PG8_SCHED;
;             PG8_LDA(At, 0, 1); PG8_STAGE(PG8_SB(0, 0), b2, voffB); PG8_STAGE(PG8_SB(0, 1), b2 + hstepB, voffB); PG8_STAGE(PG8_SA(0, 0), a2, voffA);
;             PG8_WAIT_V(8); PG8_WAIT_L(0); PG8_BAR; PG8_MMA(1, 0, At, B0); PG8_MMA(1, 1, At, B1); PG8_BAR; PG8_SCHED;
.LBB0_1455:
	s_ashr_i32 s15, s14, 31
	s_lshl_b64 s[20:21], s[14:15], 20
	s_add_u32 s24, s69, s20
	s_addc_u32 s25, s72, s21
	s_cmp_gt_i32 s93, 0
	s_cselect_b64 s[22:23], -1, 0
	s_and_b64 s[20:21], s[22:23], exec
	s_cselect_b32 s20, 0x800, 0
	s_mov_b32 s21, 0xfff80000
	s_cselect_b32 s41, -1, 0
	s_cselect_b32 s40, s21, 0x80000
	s_add_u32 s42, s24, s20
	s_addc_u32 s43, s25, 0
	s_and_b64 s[20:21], s[56:57], exec
	s_cselect_b32 s20, s43, s61
	s_cselect_b32 s21, s42, s60
	s_and_b64 s[22:23], s[56:57], s[22:23]
	s_and_b64 s[22:23], s[22:23], exec
	s_cselect_b32 s22, 0x80000, 0
	s_add_u32 s44, s28, s22
	s_addc_u32 s45, s29, 0
	s_cmp_lt_i32 s90, 0
	s_cselect_b64 s[54:55], -1, 0
	s_cmp_gt_i32 s90, -1
	s_cselect_b64 s[58:59], -1, 0
	s_and_b64 s[22:23], s[58:59], exec
	s_cselect_b32 s22, 16, 32
	s_add_u32 s23, s60, 0x100
	s_addc_u32 s24, s61, 0
	s_add_u32 s28, s38, 0x80
	s_addc_u32 s29, s39, 0
	v_lshl_add_u64 v[0:1], s[28:29], 0, v[152:153]
	v_lshl_add_u64 v[128:129], v[0:1], 0, s[36:37]
	v_lshl_add_u64 v[0:1], s[28:29], 0, v[154:155]
	v_lshl_add_u64 v[130:131], v[0:1], 0, s[36:37]
	s_lshl_b32 s25, s22, 7
	s_mov_b32 s15, 0
	s_addk_i32 s25, 0xff00
	s_mov_b64 s[60:61], 0
.Lpeel_fs:
	s_cmp_eq_u32 s25, s60
	s_cselect_b64 s[28:29], -1, 0
	s_add_i32 s15, s15, 2
	s_add_u32 s31, s38, s60
	s_addc_u32 s62, s39, s61
	s_add_u32 s31, s31, 0x100
	s_addc_u32 s94, s62, 0
	s_add_u32 s64, s23, s60
	s_addc_u32 s65, s24, s61
	s_and_b64 s[62:63], s[28:29], exec
	s_cselect_b32 s63, s20, s65
	s_cselect_b32 s62, s21, s64
	s_add_i32 s95, 0, 0x10000
	s_and_b64 s[64:65], s[28:29], exec
	v_add_u32_e32 v160, s95, v162
	s_cselect_b32 s65, s45, s94
	s_cselect_b32 s64, s44, s31
	s_add_i32 s31, 0, 0x14000
	ds_read_b128 v[132:135], v160
	ds_read_b128 v[136:139], v160 offset:1024
	ds_read_b128 v[140:143], v160 offset:2048
	ds_read_b128 v[164:167], v160 offset:3072
	v_add_u32_e32 v160, s31, v162
	ds_read_b128 v[168:171], v160
	ds_read_b128 v[172:175], v160 offset:1024
	ds_read_b128 v[176:179], v160 offset:2048
	ds_read_b128 v[180:183], v160 offset:3072
	v_lshl_add_u64 v[208:209], v[130:131], 0, s[60:61]
	s_add_i32 m0, s5, 0xc000
	ds_read_b128 v[184:187], v163
	ds_read_b128 v[188:191], v163 offset:1024
	ds_read_b128 v[192:195], v163 offset:2048
	ds_read_b128 v[196:199], v163 offset:3072
	ds_read_b128 v[200:203], v163 offset:4096
	ds_read_b128 v[204:207], v163 offset:5120
	ds_read_b128 v[214:217], v163 offset:6144
	ds_read_b128 v[218:221], v163 offset:7168
	global_load_lds_dwordx4 v[208:209], off
	v_lshl_add_u64 v[208:209], v[128:129], 0, s[60:61]
	s_add_i32 m0, s5, 0xe000
	s_nop 0
	global_load_lds_dwordx4 v[208:209], off
	s_waitcnt vmcnt(8)
	s_waitcnt lgkmcnt(0)
	s_barrier
	s_waitcnt lgkmcnt(0)
	v_mfma_f32_16x16x32_bf16 v[124:127], v[132:135], v[184:187], 0
	v_mfma_f32_16x16x32_bf16 v[124:127], v[136:139], v[188:191], v[124:127]
	v_mfma_f32_16x16x32_bf16 v[120:123], v[140:143], v[184:187], 0
	v_mfma_f32_16x16x32_bf16 v[120:123], v[164:167], v[188:191], v[120:123]
	v_mfma_f32_16x16x32_bf16 v[108:111], v[132:135], v[192:195], 0
	v_mfma_f32_16x16x32_bf16 v[108:111], v[136:139], v[196:199], v[108:111]
	v_mfma_f32_16x16x32_bf16 v[104:107], v[140:143], v[192:195], 0
	v_mfma_f32_16x16x32_bf16 v[104:107], v[164:167], v[196:199], v[104:107]
	v_mfma_f32_16x16x32_bf16 v[92:95], v[132:135], v[200:203], 0
	v_mfma_f32_16x16x32_bf16 v[92:95], v[136:139], v[204:207], v[92:95]
	v_mfma_f32_16x16x32_bf16 v[88:91], v[140:143], v[200:203], 0
	v_mfma_f32_16x16x32_bf16 v[88:91], v[164:167], v[204:207], v[88:91]
	v_mfma_f32_16x16x32_bf16 v[76:79], v[132:135], v[214:217], 0
	v_mfma_f32_16x16x32_bf16 v[76:79], v[136:139], v[218:221], v[76:79]
	v_mfma_f32_16x16x32_bf16 v[72:75], v[140:143], v[214:217], 0
	v_mfma_f32_16x16x32_bf16 v[72:75], v[164:167], v[218:221], v[72:75]
	v_mfma_f32_16x16x32_bf16 v[116:119], v[168:171], v[184:187], 0
	v_mfma_f32_16x16x32_bf16 v[116:119], v[172:175], v[188:191], v[116:119]
	v_mfma_f32_16x16x32_bf16 v[112:115], v[176:179], v[184:187], 0
	v_mfma_f32_16x16x32_bf16 v[112:115], v[180:183], v[188:191], v[112:115]
	v_mfma_f32_16x16x32_bf16 v[100:103], v[168:171], v[192:195], 0
	v_mfma_f32_16x16x32_bf16 v[100:103], v[172:175], v[196:199], v[100:103]
	v_mfma_f32_16x16x32_bf16 v[96:99], v[176:179], v[192:195], 0
	v_mfma_f32_16x16x32_bf16 v[96:99], v[180:183], v[196:199], v[96:99]
	v_mfma_f32_16x16x32_bf16 v[84:87], v[168:171], v[200:203], 0
	v_mfma_f32_16x16x32_bf16 v[84:87], v[172:175], v[204:207], v[84:87]
	v_mfma_f32_16x16x32_bf16 v[80:83], v[176:179], v[200:203], 0
	v_mfma_f32_16x16x32_bf16 v[80:83], v[180:183], v[204:207], v[80:83]
	v_mfma_f32_16x16x32_bf16 v[68:71], v[168:171], v[214:217], 0
	v_mfma_f32_16x16x32_bf16 v[68:71], v[172:175], v[218:221], v[68:71]
	v_mfma_f32_16x16x32_bf16 v[64:67], v[176:179], v[214:217], 0
	v_mfma_f32_16x16x32_bf16 v[64:67], v[180:183], v[218:221], v[64:67]
	s_barrier
	s_add_i32 s94, s95, s27
	v_lshl_add_u64 v[208:209], s[62:63], 0, v[146:147]
	s_mov_b32 m0, s94
	ds_read_b128 v[184:187], v163 offset:16384
	ds_read_b128 v[188:191], v163 offset:17408
	ds_read_b128 v[192:195], v163 offset:18432
	ds_read_b128 v[196:199], v163 offset:19456
	ds_read_b128 v[200:203], v163 offset:20480
	ds_read_b128 v[204:207], v163 offset:21504
	ds_read_b128 v[214:217], v163 offset:22528
	ds_read_b128 v[218:221], v163 offset:23552
	global_load_lds_dwordx4 v[208:209], off
	s_add_i32 m0, s94, 0x2000
	s_add_u32 s94, s62, 0x80000
	v_lshl_add_u64 v[222:223], s[62:63], 0, v[150:151]
	s_addc_u32 s95, s63, 0
	s_add_i32 s31, s31, s27
	global_load_lds_dwordx4 v[222:223], off
	v_lshl_add_u64 v[224:225], s[94:95], 0, v[146:147]
	s_mov_b32 m0, s31
	v_lshl_add_u64 v[226:227], s[64:65], 0, v[148:149]
	global_load_lds_dwordx4 v[224:225], off
	v_lshl_add_u64 v[224:225], s[94:95], 0, v[150:151]
	s_add_i32 m0, s31, 0x2000
	s_nop 0
	global_load_lds_dwordx4 v[224:225], off
	v_lshl_add_u64 v[224:225], s[64:65], 0, v[144:145]
	s_mov_b32 m0, s5
	s_nop 0
	global_load_lds_dwordx4 v[224:225], off
	s_mov_b32 m0, s53
	s_nop 0
	global_load_lds_dwordx4 v[226:227], off
	s_waitcnt vmcnt(8)
	s_waitcnt lgkmcnt(0)
	s_barrier
; #define PG8_STAGE(bufoff, gbase, voff) do { _Pragma("unroll") for (int _i = 0; _i < 2; ++_i) \
;         __builtin_amdgcn_global_load_lds((const GAS unsigned*)((const GAS char*)(gbase) + (voff)[_i]), (PG8_LAS unsigned*)(lds + (bufoff) + ldsw + _i * 8192), 16, 0, 0); } while (0)
; #define PG8_LDA(dst, b, h) do { _Pragma("unroll") for (int m = 0; m < 4; ++m) _Pragma("unroll") for (int k = 0; k < 2; ++k) dst[m][k] = *(const PG8_LAS bf16x8*)(lds + PG8_SA(b, h) + aoff + m * 2048 + k * 1024); } while (0)
; #define PG8_LDB(dst, b, h) do { _Pragma("unroll") for (int n = 0; n < 2; ++n) _Pragma("unroll") for (int k = 0; k < 2; ++k) dst[n][k] = *(const PG8_LAS bf16x8*)(lds + PG8_SB(b, h) + boff + n * 2048 + k * 1024); } while (0)
; #define PG8_MMA(ai, bj, At, Bt) do { __builtin_amdgcn_s_setprio(1); _Pragma("unroll") for (int m = 0; m < 4; ++m) _Pragma("unroll") for (int n = 0; n < 2; ++n) _Pragma("unroll") for (int k = 0; k < 2; ++k) \
;         acc[ai][bj][m][n] = __builtin_amdgcn_mfma_f32_16x16x32_bf16(Bt[n][k], At[m][k], acc[ai][bj][m][n], 0, 0, 0); __builtin_amdgcn_s_setprio(0); } while (0)
; #define PG8_WAIT_V(n) asm volatile("s_waitcnt vmcnt(" #n ")" ::: "memory")
; #define PG8_WAIT_L(n) asm volatile("s_waitcnt lgkmcnt(" #n ")" ::: "memory")
; #define PG8_BAR __builtin_amdgcn_s_barrier()
; #define PG8_SCHED __builtin_amdgcn_sched_barrier(0)
; #define PG8_STAGE(bufoff, gbase, voff) do { _Pragma("unroll") for (int _i = 0; _i < 2; ++_i) \
;         __builtin_amdgcn_global_load_lds((const GAS unsigned*)((const GAS char*)(gbase) + (voff)[_i]), (PG8_LAS unsigned*)(lds + (bufoff) + ldsw + _i * 8192), 16, 0, 0); } while (0)
; #define PG8_BAR __builtin_amdgcn_s_barrier()
; template <class Epi, class Sched, bool ALIGN_EPI = false, bool SP2 = false>
; __device__ __forceinline__ void gemm_phase(PG8_LAS unsigned char* lds, PG8_LAS unsigned char* pf, const Gemm g, const Sched& S, const Epi& E, int wv) {
;     ...
;             PG8_WAIT_V(8); PG8_WAIT_L(0); PG8_BAR; PG8_MMA(1, 0, At, B0); PG8_MMA(1, 1, At, B1); PG8_BAR; PG8_SCHED;
;             PG8_LDB(B0, 1, 0); PG8_LDB(B1, 1, 1); PG8_SCHED; PG8_LDA(At, 1, 0); PG8_STAGE(PG8_SA(0, 1), a2 + (Sched::SPLIT ? ((last && has_next) ? (nxt.kh > 0 ? -(long)hstepA : (long)hstepA) : hsA) : (long)hstepA), voffA);
;             PG8_WAIT_V(8); PG8_WAIT_L(0); PG8_BAR; PG8_MMA(0, 0, At, B0); PG8_MMA(0, 1, At, B1); PG8_BAR; PG8_SCHED;
	s_waitcnt lgkmcnt(0)
	v_mfma_f32_16x16x32_bf16 v[60:63], v[132:135], v[184:187], 0
	v_mfma_f32_16x16x32_bf16 v[60:63], v[136:139], v[188:191], v[60:63]
	v_mfma_f32_16x16x32_bf16 v[56:59], v[140:143], v[184:187], 0
	v_mfma_f32_16x16x32_bf16 v[56:59], v[164:167], v[188:191], v[56:59]
	v_mfma_f32_16x16x32_bf16 v[44:47], v[132:135], v[192:195], 0
	v_mfma_f32_16x16x32_bf16 v[44:47], v[136:139], v[196:199], v[44:47]
	v_mfma_f32_16x16x32_bf16 v[40:43], v[140:143], v[192:195], 0
	v_mfma_f32_16x16x32_bf16 v[40:43], v[164:167], v[196:199], v[40:43]
	v_mfma_f32_16x16x32_bf16 v[28:31], v[132:135], v[200:203], 0
	v_mfma_f32_16x16x32_bf16 v[28:31], v[136:139], v[204:207], v[28:31]
	v_mfma_f32_16x16x32_bf16 v[24:27], v[140:143], v[200:203], 0
	v_mfma_f32_16x16x32_bf16 v[24:27], v[164:167], v[204:207], v[24:27]
	v_mfma_f32_16x16x32_bf16 v[12:15], v[132:135], v[214:217], 0
	v_mfma_f32_16x16x32_bf16 v[12:15], v[136:139], v[218:221], v[12:15]
	v_mfma_f32_16x16x32_bf16 v[8:11], v[140:143], v[214:217], 0
	v_mfma_f32_16x16x32_bf16 v[8:11], v[164:167], v[218:221], v[8:11]
	v_mfma_f32_16x16x32_bf16 v[52:55], v[168:171], v[184:187], 0
	v_mfma_f32_16x16x32_bf16 v[52:55], v[172:175], v[188:191], v[52:55]
	v_mfma_f32_16x16x32_bf16 v[48:51], v[176:179], v[184:187], 0
	v_mfma_f32_16x16x32_bf16 v[48:51], v[180:183], v[188:191], v[48:51]
	v_mfma_f32_16x16x32_bf16 v[36:39], v[168:171], v[192:195], 0
	v_mfma_f32_16x16x32_bf16 v[36:39], v[172:175], v[196:199], v[36:39]
	v_mfma_f32_16x16x32_bf16 v[32:35], v[176:179], v[192:195], 0
	v_mfma_f32_16x16x32_bf16 v[32:35], v[180:183], v[196:199], v[32:35]
	v_mfma_f32_16x16x32_bf16 v[20:23], v[168:171], v[200:203], 0
	v_mfma_f32_16x16x32_bf16 v[20:23], v[172:175], v[204:207], v[20:23]
	v_mfma_f32_16x16x32_bf16 v[16:19], v[176:179], v[200:203], 0
	v_mfma_f32_16x16x32_bf16 v[16:19], v[180:183], v[204:207], v[16:19]
	v_mfma_f32_16x16x32_bf16 v[4:7], v[168:171], v[214:217], 0
	v_mfma_f32_16x16x32_bf16 v[4:7], v[172:175], v[218:221], v[4:7]
	v_mfma_f32_16x16x32_bf16 v[0:3], v[176:179], v[214:217], 0
	v_mfma_f32_16x16x32_bf16 v[0:3], v[180:183], v[218:221], v[0:3]
	s_barrier
	s_add_i32 s31, 0, 0x18000
	v_add_u32_e32 v160, s31, v162
	s_add_i32 s94, 0, 0x1c000
	ds_read_b128 v[132:135], v160
	ds_read_b128 v[136:139], v160 offset:1024
	ds_read_b128 v[140:143], v160 offset:2048
	ds_read_b128 v[164:167], v160 offset:3072
	v_add_u32_e32 v160, s94, v162
	ds_read_b128 v[168:171], v160
	ds_read_b128 v[172:175], v160 offset:1024
	ds_read_b128 v[176:179], v160 offset:2048
	ds_read_b128 v[180:183], v160 offset:3072
	s_and_b64 s[28:29], s[56:57], s[28:29]
	s_and_b64 s[28:29], s[28:29], exec
	s_cselect_b32 s28, s40, s36
	s_cselect_b32 s29, s41, s37
	s_add_u32 s28, s64, s28
	s_addc_u32 s29, s65, s29
	s_mov_b32 m0, s75
	v_lshl_add_u64 v[228:229], s[28:29], 0, v[144:145]
	ds_read_b128 v[184:187], v163 offset:32768
	ds_read_b128 v[188:191], v163 offset:33792
	ds_read_b128 v[192:195], v163 offset:34816
	ds_read_b128 v[196:199], v163 offset:35840
	ds_read_b128 v[200:203], v163 offset:36864
	ds_read_b128 v[204:207], v163 offset:37888
	ds_read_b128 v[214:217], v163 offset:38912
	ds_read_b128 v[218:221], v163 offset:39936
	global_load_lds_dwordx4 v[228:229], off
	v_lshl_add_u64 v[228:229], s[28:29], 0, v[148:149]
	s_mov_b32 m0, s76
	s_nop 0
	global_load_lds_dwordx4 v[228:229], off
	s_waitcnt vmcnt(8)
	s_waitcnt lgkmcnt(0)
	s_barrier
	s_waitcnt lgkmcnt(0)
	v_mfma_f32_16x16x32_bf16 v[124:127], v[132:135], v[184:187], v[124:127]
	v_mfma_f32_16x16x32_bf16 v[124:127], v[136:139], v[188:191], v[124:127]
	v_mfma_f32_16x16x32_bf16 v[120:123], v[140:143], v[184:187], v[120:123]
	v_mfma_f32_16x16x32_bf16 v[120:123], v[164:167], v[188:191], v[120:123]
	v_mfma_f32_16x16x32_bf16 v[108:111], v[132:135], v[192:195], v[108:111]
	v_mfma_f32_16x16x32_bf16 v[108:111], v[136:139], v[196:199], v[108:111]
	v_mfma_f32_16x16x32_bf16 v[104:107], v[140:143], v[192:195], v[104:107]
	v_mfma_f32_16x16x32_bf16 v[104:107], v[164:167], v[196:199], v[104:107]
	v_mfma_f32_16x16x32_bf16 v[92:95], v[132:135], v[200:203], v[92:95]
	v_mfma_f32_16x16x32_bf16 v[92:95], v[136:139], v[204:207], v[92:95]
	v_mfma_f32_16x16x32_bf16 v[88:91], v[140:143], v[200:203], v[88:91]
	v_mfma_f32_16x16x32_bf16 v[88:91], v[164:167], v[204:207], v[88:91]
	v_mfma_f32_16x16x32_bf16 v[76:79], v[132:135], v[214:217], v[76:79]
	v_mfma_f32_16x16x32_bf16 v[76:79], v[136:139], v[218:221], v[76:79]
	v_mfma_f32_16x16x32_bf16 v[72:75], v[140:143], v[214:217], v[72:75]
	v_mfma_f32_16x16x32_bf16 v[72:75], v[164:167], v[218:221], v[72:75]
	v_mfma_f32_16x16x32_bf16 v[116:119], v[168:171], v[184:187], v[116:119]
	v_mfma_f32_16x16x32_bf16 v[116:119], v[172:175], v[188:191], v[116:119]
	v_mfma_f32_16x16x32_bf16 v[112:115], v[176:179], v[184:187], v[112:115]
	v_mfma_f32_16x16x32_bf16 v[112:115], v[180:183], v[188:191], v[112:115]
	v_mfma_f32_16x16x32_bf16 v[100:103], v[168:171], v[192:195], v[100:103]
	v_mfma_f32_16x16x32_bf16 v[100:103], v[172:175], v[196:199], v[100:103]
	v_mfma_f32_16x16x32_bf16 v[96:99], v[176:179], v[192:195], v[96:99]
	v_mfma_f32_16x16x32_bf16 v[96:99], v[180:183], v[196:199], v[96:99]
	v_mfma_f32_16x16x32_bf16 v[84:87], v[168:171], v[200:203], v[84:87]
	v_mfma_f32_16x16x32_bf16 v[84:87], v[172:175], v[204:207], v[84:87]
	v_mfma_f32_16x16x32_bf16 v[80:83], v[176:179], v[200:203], v[80:83]
	v_mfma_f32_16x16x32_bf16 v[80:83], v[180:183], v[204:207], v[80:83]
	v_mfma_f32_16x16x32_bf16 v[68:71], v[168:171], v[214:217], v[68:71]
	v_mfma_f32_16x16x32_bf16 v[68:71], v[172:175], v[218:221], v[68:71]
	v_mfma_f32_16x16x32_bf16 v[64:67], v[176:179], v[214:217], v[64:67]
	v_mfma_f32_16x16x32_bf16 v[64:67], v[180:183], v[218:221], v[64:67]
	s_barrier
; #define PG8_STAGE(bufoff, gbase, voff) do { _Pragma("unroll") for (int _i = 0; _i < 2; ++_i) \
;         __builtin_amdgcn_global_load_lds((const GAS unsigned*)((const GAS char*)(gbase) + (voff)[_i]), (PG8_LAS unsigned*)(lds + (bufoff) + ldsw + _i * 8192), 16, 0, 0); } while (0)
; #define PG8_LDA(dst, b, h) do { _Pragma("unroll") for (int m = 0; m < 4; ++m) _Pragma("unroll") for (int k = 0; k < 2; ++k) dst[m][k] = *(const PG8_LAS bf16x8*)(lds + PG8_SA(b, h) + aoff + m * 2048 + k * 1024); } while (0)
; #define PG8_MMA(ai, bj, At, Bt) do { __builtin_amdgcn_s_setprio(1); _Pragma("unroll") for (int m = 0; m < 4; ++m) _Pragma("unroll") for (int n = 0; n < 2; ++n) _Pragma("unroll") for (int k = 0; k < 2; ++k) \
;         acc[ai][bj][m][n] = __builtin_amdgcn_mfma_f32_16x16x32_bf16(Bt[n][k], At[m][k], acc[ai][bj][m][n], 0, 0, 0); __builtin_amdgcn_s_setprio(0); } while (0)
; #define PG8_WAIT_V(n) asm volatile("s_waitcnt vmcnt(" #n ")" ::: "memory")
; #define PG8_WAIT_L(n) asm volatile("s_waitcnt lgkmcnt(" #n ")" ::: "memory")
; #define PG8_BAR __builtin_amdgcn_s_barrier()
; #define PG8_SCHED __builtin_amdgcn_sched_barrier(0)
; #define PG8_STAGE(bufoff, gbase, voff) do { _Pragma("unroll") for (int _i = 0; _i < 2; ++_i) \
;         __builtin_amdgcn_global_load_lds((const GAS unsigned*)((const GAS char*)(gbase) + (voff)[_i]), (PG8_LAS unsigned*)(lds + (bufoff) + ldsw + _i * 8192), 16, 0, 0); } while (0)
; #define PG8_LDA(dst, b, h) do { _Pragma("unroll") for (int m = 0; m < 4; ++m) _Pragma("unroll") for (int k = 0; k < 2; ++k) dst[m][k] = *(const PG8_LAS bf16x8*)(lds + PG8_SA(b, h) + aoff + m * 2048 + k * 1024); } while (0)
; #define PG8_WAIT_V(n) asm volatile("s_waitcnt vmcnt(" #n ")" ::: "memory")
; #define PG8_WAIT_L(n) asm volatile("s_waitcnt lgkmcnt(" #n ")" ::: "memory")
; #define PG8_BAR __builtin_amdgcn_s_barrier()
; #define PG8_SCHED __builtin_amdgcn_sched_barrier(0)
; template <class Epi, class Sched, bool ALIGN_EPI = false, bool SP2 = false>
; __device__ __forceinline__ void gemm_phase(PG8_LAS unsigned char* lds, PG8_LAS unsigned char* pf, const Gemm g, const Sched& S, const Epi& E, int wv) {
;     ...
;             PG8_LDA(At, 1, 1); PG8_STAGE(PG8_SB(1, 0), b3, voffB); PG8_STAGE(PG8_SB(1, 1), b3 + hstepB, voffB); PG8_STAGE(PG8_SA(1, 0), a3, voffA);
;             PG8_WAIT_V(8); PG8_WAIT_L(0); PG8_BAR; PG8_MMA(1, 0, At, B0); PG8_MMA(1, 1, At, B1); PG8_BAR; PG8_SCHED;
	s_add_i32 s28, s31, s27
	v_lshl_add_u64 v[208:209], v[208:209], 0, s[16:17]
	s_mov_b32 m0, s28
	ds_read_b128 v[184:187], v163 offset:49152
	ds_read_b128 v[188:191], v163 offset:50176
	ds_read_b128 v[192:195], v163 offset:51200
	ds_read_b128 v[196:199], v163 offset:52224
	ds_read_b128 v[200:203], v163 offset:53248
	ds_read_b128 v[204:207], v163 offset:54272
	ds_read_b128 v[214:217], v163 offset:55296
	ds_read_b128 v[218:221], v163 offset:56320
	global_load_lds_dwordx4 v[208:209], off
	s_add_i32 m0, s28, 0x2000
	s_add_u32 s28, s62, 0x80080
	v_lshl_add_u64 v[208:209], v[222:223], 0, s[16:17]
	s_addc_u32 s29, s63, 0
	s_add_i32 s31, s94, s27
	global_load_lds_dwordx4 v[208:209], off
	v_lshl_add_u64 v[208:209], s[28:29], 0, v[146:147]
	s_mov_b32 m0, s31
	s_nop 0
	global_load_lds_dwordx4 v[208:209], off
	v_lshl_add_u64 v[208:209], s[28:29], 0, v[150:151]
	s_add_i32 m0, s31, 0x2000
	s_nop 0
	global_load_lds_dwordx4 v[208:209], off
	v_lshl_add_u64 v[208:209], v[224:225], 0, s[16:17]
	s_mov_b32 m0, s77
	s_nop 0
	global_load_lds_dwordx4 v[208:209], off
	v_lshl_add_u64 v[208:209], v[226:227], 0, s[16:17]
	s_mov_b32 m0, s78
	s_nop 0
	global_load_lds_dwordx4 v[208:209], off
	s_waitcnt vmcnt(8)
	s_waitcnt lgkmcnt(0)
	s_barrier
	s_waitcnt lgkmcnt(0)
	v_mfma_f32_16x16x32_bf16 v[60:63], v[132:135], v[184:187], v[60:63]
	v_mfma_f32_16x16x32_bf16 v[60:63], v[136:139], v[188:191], v[60:63]
	v_mfma_f32_16x16x32_bf16 v[56:59], v[140:143], v[184:187], v[56:59]
	v_mfma_f32_16x16x32_bf16 v[56:59], v[164:167], v[188:191], v[56:59]
	v_mfma_f32_16x16x32_bf16 v[44:47], v[132:135], v[192:195], v[44:47]
	v_mfma_f32_16x16x32_bf16 v[44:47], v[136:139], v[196:199], v[44:47]
	v_mfma_f32_16x16x32_bf16 v[40:43], v[140:143], v[192:195], v[40:43]
	v_mfma_f32_16x16x32_bf16 v[40:43], v[164:167], v[196:199], v[40:43]
	v_mfma_f32_16x16x32_bf16 v[28:31], v[132:135], v[200:203], v[28:31]
	v_mfma_f32_16x16x32_bf16 v[28:31], v[136:139], v[204:207], v[28:31]
	v_mfma_f32_16x16x32_bf16 v[24:27], v[140:143], v[200:203], v[24:27]
	v_mfma_f32_16x16x32_bf16 v[24:27], v[164:167], v[204:207], v[24:27]
	v_mfma_f32_16x16x32_bf16 v[12:15], v[132:135], v[214:217], v[12:15]
	v_mfma_f32_16x16x32_bf16 v[12:15], v[136:139], v[218:221], v[12:15]
	v_mfma_f32_16x16x32_bf16 v[8:11], v[140:143], v[214:217], v[8:11]
	v_mfma_f32_16x16x32_bf16 v[8:11], v[164:167], v[218:221], v[8:11]
	v_mfma_f32_16x16x32_bf16 v[52:55], v[168:171], v[184:187], v[52:55]
	v_mfma_f32_16x16x32_bf16 v[52:55], v[172:175], v[188:191], v[52:55]
	v_mfma_f32_16x16x32_bf16 v[48:51], v[176:179], v[184:187], v[48:51]
	v_mfma_f32_16x16x32_bf16 v[48:51], v[180:183], v[188:191], v[48:51]
	v_mfma_f32_16x16x32_bf16 v[36:39], v[168:171], v[192:195], v[36:39]
	v_mfma_f32_16x16x32_bf16 v[36:39], v[172:175], v[196:199], v[36:39]
	v_mfma_f32_16x16x32_bf16 v[32:35], v[176:179], v[192:195], v[32:35]
	v_mfma_f32_16x16x32_bf16 v[32:35], v[180:183], v[196:199], v[32:35]
	v_mfma_f32_16x16x32_bf16 v[20:23], v[168:171], v[200:203], v[20:23]
	v_mfma_f32_16x16x32_bf16 v[20:23], v[172:175], v[204:207], v[20:23]
	v_mfma_f32_16x16x32_bf16 v[16:19], v[176:179], v[200:203], v[16:19]
	v_mfma_f32_16x16x32_bf16 v[16:19], v[180:183], v[204:207], v[16:19]
	v_mfma_f32_16x16x32_bf16 v[4:7], v[168:171], v[214:217], v[4:7]
	v_mfma_f32_16x16x32_bf16 v[4:7], v[172:175], v[218:221], v[4:7]
	v_mfma_f32_16x16x32_bf16 v[0:3], v[176:179], v[214:217], v[0:3]
	v_mfma_f32_16x16x32_bf16 v[0:3], v[180:183], v[218:221], v[0:3]
	s_barrier
	s_add_u32 s60, s60, 0x100
	s_addc_u32 s61, s61, 0
	s_cmp_ge_u32 s15, s22

; #define GAS __attribute__((address_space(1)))
; #define PG8_STAGE(bufoff, gbase, voff) do { _Pragma("unroll") for (int _i = 0; _i < 2; ++_i) \
;         __builtin_amdgcn_global_load_lds((const GAS unsigned*)((const GAS char*)(gbase) + (voff)[_i]), (PG8_LAS unsigned*)(lds + (bufoff) + ldsw + _i * 8192), 16, 0, 0); } while (0)
; #define PG8_LDA(dst, b, h) do { _Pragma("unroll") for (int m = 0; m < 4; ++m) _Pragma("unroll") for (int k = 0; k < 2; ++k) dst[m][k] = *(const PG8_LAS bf16x8*)(lds + PG8_SA(b, h) + aoff + m * 2048 + k * 1024); } while (0)
; #define PG8_LDB(dst, b, h) do { _Pragma("unroll") for (int n = 0; n < 2; ++n) _Pragma("unroll") for (int k = 0; k < 2; ++k) dst[n][k] = *(const PG8_LAS bf16x8*)(lds + PG8_SB(b, h) + boff + n * 2048 + k * 1024); } while (0)
; template <class Epi, class Sched, bool ALIGN_EPI = false, bool SP2 = false>
; __device__ __forceinline__ void gemm_phase(PG8_LAS unsigned char* lds, PG8_LAS unsigned char* pf, const Gemm g, const Sched& S, const Epi& E, int wv) {
;     ...
;         const bool has_next = S.next(ui + 1, nxt);
;         const GAS char* nA = has_next ? PG8_ABASE(nxt) : cA; const GAS char* nB = has_next ? PG8_BBASE(nxt) : cB;
;         if constexpr (Sched::SPLIT) { if (has_next && nxt.kh > 0) nA += hstepA; }
;         int ntu = nt; if constexpr (Sched::SPLIT) { if (cur.kh >= 0) ntu = nt >> 1; }
;         for (int t = 0; t < ntu; t += 2) {
;             const bool last = (t == ntu - 2);
;             const GAS char* a1 = cA + (size_t)(t + 1) * kstep;
;             const GAS char* a2 = last ? nA : cA + (size_t)(t + 2) * kstep; const GAS char* b2 = last ? nB : cB + (size_t)(t + 2) * kstep;
;             const GAS char* a3 = a2 + kstep; const GAS char* b3 = b2 + kstep;
;             if (last && has_next) S.a_ready(nxt);
;             if constexpr (SP2) {
;             PG8_LDB(B0, 0, 0); PG8_LDB(B1, 0, 1); PG8_SCHED; PG8_LDA(At, 0, 0); PG8_STAGE(PG8_SA(1, 1), a1 + (Sched::SPLIT ? hsA : (long)hstepA), voffA);
;             PG8_WAIT_V(8); PG8_WAIT_L(0); PG8_BAR; PG8_MMA(0, 0, At, B0); PG8_MMA(0, 1, At, B1); PG8_BAR; PG8_SCHED;
;             PG8_LDA(At, 0, 1); PG8_STAGE(PG8_SB(0, 0), b2, voffB); PG8_STAGE(PG8_SB(0, 1), b2 + hstepB, voffB); PG8_STAGE(PG8_SA(0, 0), a2, voffA);
;             PG8_WAIT_V(8); PG8_WAIT_L(0); PG8_BAR; PG8_MMA(1, 0, At, B0); PG8_MMA(1, 1, At, B1); PG8_BAR; PG8_SCHED;
.LBB0_1724:
	s_add_u32 s20, s12, 0x100
	s_addc_u32 s21, s13, 0
	s_mov_b32 s22, -2
.Lpeel_fd:
	s_add_u32 s12, s10, 0x100
	s_addc_u32 s13, s11, 0
	s_add_i32 s23, 0, 0x10000
	s_cmpk_eq_i32 s22, 0x54
	s_cselect_b32 s29, s5, s13
	s_cselect_b32 s28, s4, s12
	s_cselect_b32 s15, s7, s21
	s_cselect_b32 s14, s6, s20
	s_add_i32 s24, 0, 0x14000
	v_add_u32_e32 v140, s23, v170
	v_add_u32_e32 v172, s24, v170
	ds_read_b128 v[128:131], v140
	ds_read_b128 v[132:135], v140 offset:1024
	ds_read_b128 v[136:139], v140 offset:2048
	ds_read_b128 v[140:143], v140 offset:3072
	ds_read_b128 v[144:147], v172
	ds_read_b128 v[148:151], v172 offset:1024
	ds_read_b128 v[152:155], v172 offset:2048
	ds_read_b128 v[172:175], v172 offset:3072
	v_lshl_add_u64 v[208:209], s[10:11], 0, v[166:167]
	s_add_i32 m0, s27, 0xc000
	ds_read_b128 v[176:179], v171
	ds_read_b128 v[180:183], v171 offset:1024
	ds_read_b128 v[184:187], v171 offset:2048
	ds_read_b128 v[188:191], v171 offset:3072
	ds_read_b128 v[192:195], v171 offset:4096
	ds_read_b128 v[196:199], v171 offset:5120
	ds_read_b128 v[200:203], v171 offset:6144
	ds_read_b128 v[204:207], v171 offset:7168
	global_load_lds_dwordx4 v[208:209], off
	v_lshl_add_u64 v[208:209], s[10:11], 0, v[164:165]
	s_add_i32 m0, s27, 0xe000
	s_nop 0
	global_load_lds_dwordx4 v[208:209], off
	s_waitcnt vmcnt(8)
	s_waitcnt lgkmcnt(0)
	s_barrier
	s_waitcnt lgkmcnt(0)
	v_mfma_f32_16x16x32_bf16 v[124:127], v[128:131], v[176:179], 0
	v_mfma_f32_16x16x32_bf16 v[124:127], v[132:135], v[180:183], v[124:127]
	v_mfma_f32_16x16x32_bf16 v[120:123], v[136:139], v[176:179], 0
	v_mfma_f32_16x16x32_bf16 v[120:123], v[140:143], v[180:183], v[120:123]
	v_mfma_f32_16x16x32_bf16 v[116:119], v[128:131], v[184:187], 0
	v_mfma_f32_16x16x32_bf16 v[116:119], v[132:135], v[188:191], v[116:119]
	v_mfma_f32_16x16x32_bf16 v[112:115], v[136:139], v[184:187], 0
	v_mfma_f32_16x16x32_bf16 v[112:115], v[140:143], v[188:191], v[112:115]
	v_mfma_f32_16x16x32_bf16 v[108:111], v[128:131], v[192:195], 0
	v_mfma_f32_16x16x32_bf16 v[108:111], v[132:135], v[196:199], v[108:111]
	v_mfma_f32_16x16x32_bf16 v[104:107], v[136:139], v[192:195], 0
	v_mfma_f32_16x16x32_bf16 v[104:107], v[140:143], v[196:199], v[104:107]
	v_mfma_f32_16x16x32_bf16 v[100:103], v[128:131], v[200:203], 0
	v_mfma_f32_16x16x32_bf16 v[100:103], v[132:135], v[204:207], v[100:103]
	v_mfma_f32_16x16x32_bf16 v[96:99], v[136:139], v[200:203], 0
	v_mfma_f32_16x16x32_bf16 v[96:99], v[140:143], v[204:207], v[96:99]
	v_mfma_f32_16x16x32_bf16 v[60:63], v[144:147], v[176:179], 0
	v_mfma_f32_16x16x32_bf16 v[60:63], v[148:151], v[180:183], v[60:63]
	v_mfma_f32_16x16x32_bf16 v[56:59], v[152:155], v[176:179], 0
	v_mfma_f32_16x16x32_bf16 v[56:59], v[172:175], v[180:183], v[56:59]
	v_mfma_f32_16x16x32_bf16 v[52:55], v[144:147], v[184:187], 0
	v_mfma_f32_16x16x32_bf16 v[52:55], v[148:151], v[188:191], v[52:55]
	v_mfma_f32_16x16x32_bf16 v[48:51], v[152:155], v[184:187], 0
	v_mfma_f32_16x16x32_bf16 v[48:51], v[172:175], v[188:191], v[48:51]
	v_mfma_f32_16x16x32_bf16 v[44:47], v[144:147], v[192:195], 0
	v_mfma_f32_16x16x32_bf16 v[44:47], v[148:151], v[196:199], v[44:47]
	v_mfma_f32_16x16x32_bf16 v[40:43], v[152:155], v[192:195], 0
	v_mfma_f32_16x16x32_bf16 v[40:43], v[172:175], v[196:199], v[40:43]
	v_mfma_f32_16x16x32_bf16 v[36:39], v[144:147], v[200:203], 0
	v_mfma_f32_16x16x32_bf16 v[36:39], v[148:151], v[204:207], v[36:39]
	v_mfma_f32_16x16x32_bf16 v[32:35], v[152:155], v[200:203], 0
	v_mfma_f32_16x16x32_bf16 v[32:35], v[172:175], v[204:207], v[32:35]
	s_barrier
	s_add_i32 s10, s23, s19
	v_lshl_add_u64 v[208:209], s[14:15], 0, v[160:161]
	s_mov_b32 m0, s10
	ds_read_b128 v[176:179], v171 offset:16384
	ds_read_b128 v[180:183], v171 offset:17408
	ds_read_b128 v[184:187], v171 offset:18432
	ds_read_b128 v[188:191], v171 offset:19456
	ds_read_b128 v[192:195], v171 offset:20480
	ds_read_b128 v[196:199], v171 offset:21504
	ds_read_b128 v[200:203], v171 offset:22528
	ds_read_b128 v[204:207], v171 offset:23552
	global_load_lds_dwordx4 v[208:209], off
	s_add_i32 m0, s10, 0x2000
	s_add_u32 s10, s14, 0x160000
	v_lshl_add_u64 v[214:215], s[14:15], 0, v[162:163]
	s_addc_u32 s11, s15, 0
	s_add_i32 s23, s24, s19
	global_load_lds_dwordx4 v[214:215], off
	v_lshl_add_u64 v[216:217], s[10:11], 0, v[160:161]
	s_mov_b32 m0, s23
	v_lshl_add_u64 v[218:219], s[28:29], 0, v[158:159]
	global_load_lds_dwordx4 v[216:217], off
	v_lshl_add_u64 v[216:217], s[10:11], 0, v[162:163]
	s_add_i32 m0, s23, 0x2000
	s_nop 0
	global_load_lds_dwordx4 v[216:217], off
	v_lshl_add_u64 v[216:217], s[28:29], 0, v[156:157]
	s_mov_b32 m0, s27
	s_nop 0
	global_load_lds_dwordx4 v[216:217], off
	s_mov_b32 m0, s30
	s_nop 0
	global_load_lds_dwordx4 v[218:219], off
	s_waitcnt vmcnt(8)
	s_waitcnt lgkmcnt(0)
	s_barrier
; #define PG8_STAGE(bufoff, gbase, voff) do { _Pragma("unroll") for (int _i = 0; _i < 2; ++_i) \
;         __builtin_amdgcn_global_load_lds((const GAS unsigned*)((const GAS char*)(gbase) + (voff)[_i]), (PG8_LAS unsigned*)(lds + (bufoff) + ldsw + _i * 8192), 16, 0, 0); } while (0)
; #define PG8_LDA(dst, b, h) do { _Pragma("unroll") for (int m = 0; m < 4; ++m) _Pragma("unroll") for (int k = 0; k < 2; ++k) dst[m][k] = *(const PG8_LAS bf16x8*)(lds + PG8_SA(b, h) + aoff + m * 2048 + k * 1024); } while (0)
; #define PG8_LDB(dst, b, h) do { _Pragma("unroll") for (int n = 0; n < 2; ++n) _Pragma("unroll") for (int k = 0; k < 2; ++k) dst[n][k] = *(const PG8_LAS bf16x8*)(lds + PG8_SB(b, h) + boff + n * 2048 + k * 1024); } while (0)
; #define PG8_MMA(ai, bj, At, Bt) do { __builtin_amdgcn_s_setprio(1); _Pragma("unroll") for (int m = 0; m < 4; ++m) _Pragma("unroll") for (int n = 0; n < 2; ++n) _Pragma("unroll") for (int k = 0; k < 2; ++k) \
;         acc[ai][bj][m][n] = __builtin_amdgcn_mfma_f32_16x16x32_bf16(Bt[n][k], At[m][k], acc[ai][bj][m][n], 0, 0, 0); __builtin_amdgcn_s_setprio(0); } while (0)
; #define PG8_WAIT_V(n) asm volatile("s_waitcnt vmcnt(" #n ")" ::: "memory")
; #define PG8_WAIT_L(n) asm volatile("s_waitcnt lgkmcnt(" #n ")" ::: "memory")
; #define PG8_BAR __builtin_amdgcn_s_barrier()
; #define PG8_SCHED __builtin_amdgcn_sched_barrier(0)
; #define PG8_STAGE(bufoff, gbase, voff) do { _Pragma("unroll") for (int _i = 0; _i < 2; ++_i) \
;         __builtin_amdgcn_global_load_lds((const GAS unsigned*)((const GAS char*)(gbase) + (voff)[_i]), (PG8_LAS unsigned*)(lds + (bufoff) + ldsw + _i * 8192), 16, 0, 0); } while (0)
; #define PG8_BAR __builtin_amdgcn_s_barrier()
; template <class Epi, class Sched, bool ALIGN_EPI = false, bool SP2 = false>
; __device__ __forceinline__ void gemm_phase(PG8_LAS unsigned char* lds, PG8_LAS unsigned char* pf, const Gemm g, const Sched& S, const Epi& E, int wv) {
;     ...
;             PG8_WAIT_V(8); PG8_WAIT_L(0); PG8_BAR; PG8_MMA(1, 0, At, B0); PG8_MMA(1, 1, At, B1); PG8_BAR; PG8_SCHED;
;             PG8_LDB(B0, 1, 0); PG8_LDB(B1, 1, 1); PG8_SCHED; PG8_LDA(At, 1, 0); PG8_STAGE(PG8_SA(0, 1), a2 + (Sched::SPLIT ? ((last && has_next) ? (nxt.kh > 0 ? -(long)hstepA : (long)hstepA) : hsA) : (long)hstepA), voffA);
;             PG8_WAIT_V(8); PG8_WAIT_L(0); PG8_BAR; PG8_MMA(0, 0, At, B0); PG8_MMA(0, 1, At, B1); PG8_BAR; PG8_SCHED;
	s_waitcnt lgkmcnt(0)
	v_mfma_f32_16x16x32_bf16 v[92:95], v[128:131], v[176:179], 0
	v_mfma_f32_16x16x32_bf16 v[92:95], v[132:135], v[180:183], v[92:95]
	v_mfma_f32_16x16x32_bf16 v[88:91], v[136:139], v[176:179], 0
	v_mfma_f32_16x16x32_bf16 v[88:91], v[140:143], v[180:183], v[88:91]
	v_mfma_f32_16x16x32_bf16 v[84:87], v[128:131], v[184:187], 0
	v_mfma_f32_16x16x32_bf16 v[84:87], v[132:135], v[188:191], v[84:87]
	v_mfma_f32_16x16x32_bf16 v[80:83], v[136:139], v[184:187], 0
	v_mfma_f32_16x16x32_bf16 v[80:83], v[140:143], v[188:191], v[80:83]
	v_mfma_f32_16x16x32_bf16 v[76:79], v[128:131], v[192:195], 0
	v_mfma_f32_16x16x32_bf16 v[76:79], v[132:135], v[196:199], v[76:79]
	v_mfma_f32_16x16x32_bf16 v[72:75], v[136:139], v[192:195], 0
	v_mfma_f32_16x16x32_bf16 v[72:75], v[140:143], v[196:199], v[72:75]
	v_mfma_f32_16x16x32_bf16 v[68:71], v[128:131], v[200:203], 0
	v_mfma_f32_16x16x32_bf16 v[68:71], v[132:135], v[204:207], v[68:71]
	v_mfma_f32_16x16x32_bf16 v[64:67], v[136:139], v[200:203], 0
	v_mfma_f32_16x16x32_bf16 v[64:67], v[140:143], v[204:207], v[64:67]
	v_mfma_f32_16x16x32_bf16 v[28:31], v[144:147], v[176:179], 0
	v_mfma_f32_16x16x32_bf16 v[28:31], v[148:151], v[180:183], v[28:31]
	v_mfma_f32_16x16x32_bf16 v[24:27], v[152:155], v[176:179], 0
	v_mfma_f32_16x16x32_bf16 v[24:27], v[172:175], v[180:183], v[24:27]
	v_mfma_f32_16x16x32_bf16 v[20:23], v[144:147], v[184:187], 0
	v_mfma_f32_16x16x32_bf16 v[20:23], v[148:151], v[188:191], v[20:23]
	v_mfma_f32_16x16x32_bf16 v[16:19], v[152:155], v[184:187], 0
	v_mfma_f32_16x16x32_bf16 v[16:19], v[172:175], v[188:191], v[16:19]
	v_mfma_f32_16x16x32_bf16 v[12:15], v[144:147], v[192:195], 0
	v_mfma_f32_16x16x32_bf16 v[12:15], v[148:151], v[196:199], v[12:15]
	v_mfma_f32_16x16x32_bf16 v[8:11], v[152:155], v[192:195], 0
	v_mfma_f32_16x16x32_bf16 v[8:11], v[172:175], v[196:199], v[8:11]
	v_mfma_f32_16x16x32_bf16 v[4:7], v[144:147], v[200:203], 0
	v_mfma_f32_16x16x32_bf16 v[4:7], v[148:151], v[204:207], v[4:7]
	v_mfma_f32_16x16x32_bf16 v[0:3], v[152:155], v[200:203], 0
	v_mfma_f32_16x16x32_bf16 v[0:3], v[172:175], v[204:207], v[0:3]
	s_barrier
	s_add_i32 s23, 0, 0x18000
	s_add_i32 s24, 0, 0x1c000
	v_add_u32_e32 v140, s23, v170
	v_add_u32_e32 v172, s24, v170
	ds_read_b128 v[128:131], v140
	ds_read_b128 v[132:135], v140 offset:1024
	ds_read_b128 v[136:139], v140 offset:2048
	ds_read_b128 v[140:143], v140 offset:3072
	ds_read_b128 v[144:147], v172
	ds_read_b128 v[148:151], v172 offset:1024
	ds_read_b128 v[152:155], v172 offset:2048
	ds_read_b128 v[172:175], v172 offset:3072
	s_add_u32 s10, s28, 0x160000
	s_addc_u32 s11, s29, 0
	s_mov_b32 m0, s31
	v_lshl_add_u64 v[220:221], s[10:11], 0, v[156:157]
	ds_read_b128 v[176:179], v171 offset:32768
	ds_read_b128 v[180:183], v171 offset:33792
	ds_read_b128 v[184:187], v171 offset:34816
	ds_read_b128 v[188:191], v171 offset:35840
	ds_read_b128 v[192:195], v171 offset:36864
	ds_read_b128 v[196:199], v171 offset:37888
	ds_read_b128 v[200:203], v171 offset:38912
	ds_read_b128 v[204:207], v171 offset:39936
	global_load_lds_dwordx4 v[220:221], off
	v_lshl_add_u64 v[220:221], s[10:11], 0, v[158:159]
	s_mov_b32 m0, s38
	s_nop 0
	global_load_lds_dwordx4 v[220:221], off
	s_waitcnt vmcnt(8)
	s_waitcnt lgkmcnt(0)
	s_barrier
	s_waitcnt lgkmcnt(0)
	v_mfma_f32_16x16x32_bf16 v[124:127], v[128:131], v[176:179], v[124:127]
	v_mfma_f32_16x16x32_bf16 v[124:127], v[132:135], v[180:183], v[124:127]
	v_mfma_f32_16x16x32_bf16 v[120:123], v[136:139], v[176:179], v[120:123]
	v_mfma_f32_16x16x32_bf16 v[120:123], v[140:143], v[180:183], v[120:123]
	v_mfma_f32_16x16x32_bf16 v[116:119], v[128:131], v[184:187], v[116:119]
	v_mfma_f32_16x16x32_bf16 v[116:119], v[132:135], v[188:191], v[116:119]
	v_mfma_f32_16x16x32_bf16 v[112:115], v[136:139], v[184:187], v[112:115]
	v_mfma_f32_16x16x32_bf16 v[112:115], v[140:143], v[188:191], v[112:115]
	v_mfma_f32_16x16x32_bf16 v[108:111], v[128:131], v[192:195], v[108:111]
	v_mfma_f32_16x16x32_bf16 v[108:111], v[132:135], v[196:199], v[108:111]
	v_mfma_f32_16x16x32_bf16 v[104:107], v[136:139], v[192:195], v[104:107]
	v_mfma_f32_16x16x32_bf16 v[104:107], v[140:143], v[196:199], v[104:107]
	v_mfma_f32_16x16x32_bf16 v[100:103], v[128:131], v[200:203], v[100:103]
	v_mfma_f32_16x16x32_bf16 v[100:103], v[132:135], v[204:207], v[100:103]
	v_mfma_f32_16x16x32_bf16 v[96:99], v[136:139], v[200:203], v[96:99]
	v_mfma_f32_16x16x32_bf16 v[96:99], v[140:143], v[204:207], v[96:99]
	v_mfma_f32_16x16x32_bf16 v[60:63], v[144:147], v[176:179], v[60:63]
	v_mfma_f32_16x16x32_bf16 v[60:63], v[148:151], v[180:183], v[60:63]
	v_mfma_f32_16x16x32_bf16 v[56:59], v[152:155], v[176:179], v[56:59]
	v_mfma_f32_16x16x32_bf16 v[56:59], v[172:175], v[180:183], v[56:59]
	v_mfma_f32_16x16x32_bf16 v[52:55], v[144:147], v[184:187], v[52:55]
	v_mfma_f32_16x16x32_bf16 v[52:55], v[148:151], v[188:191], v[52:55]
	v_mfma_f32_16x16x32_bf16 v[48:51], v[152:155], v[184:187], v[48:51]
	v_mfma_f32_16x16x32_bf16 v[48:51], v[172:175], v[188:191], v[48:51]
	v_mfma_f32_16x16x32_bf16 v[44:47], v[144:147], v[192:195], v[44:47]
	v_mfma_f32_16x16x32_bf16 v[44:47], v[148:151], v[196:199], v[44:47]
	v_mfma_f32_16x16x32_bf16 v[40:43], v[152:155], v[192:195], v[40:43]
	v_mfma_f32_16x16x32_bf16 v[40:43], v[172:175], v[196:199], v[40:43]
	v_mfma_f32_16x16x32_bf16 v[36:39], v[144:147], v[200:203], v[36:39]
	v_mfma_f32_16x16x32_bf16 v[36:39], v[148:151], v[204:207], v[36:39]
	v_mfma_f32_16x16x32_bf16 v[32:35], v[152:155], v[200:203], v[32:35]
	v_mfma_f32_16x16x32_bf16 v[32:35], v[172:175], v[204:207], v[32:35]
	s_barrier
; #define GAS __attribute__((address_space(1)))
; #define PG8_STAGE(bufoff, gbase, voff) do { _Pragma("unroll") for (int _i = 0; _i < 2; ++_i) \
;         __builtin_amdgcn_global_load_lds((const GAS unsigned*)((const GAS char*)(gbase) + (voff)[_i]), (PG8_LAS unsigned*)(lds + (bufoff) + ldsw + _i * 8192), 16, 0, 0); } while (0)
; #define PG8_LDA(dst, b, h) do { _Pragma("unroll") for (int m = 0; m < 4; ++m) _Pragma("unroll") for (int k = 0; k < 2; ++k) dst[m][k] = *(const PG8_LAS bf16x8*)(lds + PG8_SA(b, h) + aoff + m * 2048 + k * 1024); } while (0)
; #define PG8_MMA(ai, bj, At, Bt) do { __builtin_amdgcn_s_setprio(1); _Pragma("unroll") for (int m = 0; m < 4; ++m) _Pragma("unroll") for (int n = 0; n < 2; ++n) _Pragma("unroll") for (int k = 0; k < 2; ++k) \
;         acc[ai][bj][m][n] = __builtin_amdgcn_mfma_f32_16x16x32_bf16(Bt[n][k], At[m][k], acc[ai][bj][m][n], 0, 0, 0); __builtin_amdgcn_s_setprio(0); } while (0)
; #define PG8_WAIT_V(n) asm volatile("s_waitcnt vmcnt(" #n ")" ::: "memory")
; #define PG8_WAIT_L(n) asm volatile("s_waitcnt lgkmcnt(" #n ")" ::: "memory")
; #define PG8_BAR __builtin_amdgcn_s_barrier()
; #define PG8_SCHED __builtin_amdgcn_sched_barrier(0)
; #define PG8_STAGE(bufoff, gbase, voff) do { _Pragma("unroll") for (int _i = 0; _i < 2; ++_i) \
;         __builtin_amdgcn_global_load_lds((const GAS unsigned*)((const GAS char*)(gbase) + (voff)[_i]), (PG8_LAS unsigned*)(lds + (bufoff) + ldsw + _i * 8192), 16, 0, 0); } while (0)
; #define PG8_LDA(dst, b, h) do { _Pragma("unroll") for (int m = 0; m < 4; ++m) _Pragma("unroll") for (int k = 0; k < 2; ++k) dst[m][k] = *(const PG8_LAS bf16x8*)(lds + PG8_SA(b, h) + aoff + m * 2048 + k * 1024); } while (0)
; #define PG8_BAR __builtin_amdgcn_s_barrier()
; template <class Epi, class Sched, bool ALIGN_EPI = false, bool SP2 = false>
; __device__ __forceinline__ void gemm_phase(PG8_LAS unsigned char* lds, PG8_LAS unsigned char* pf, const Gemm g, const Sched& S, const Epi& E, int wv) {
;     ...
;         for (int t = 0; t < ntu; t += 2) {
;             const bool last = (t == ntu - 2);
;             const GAS char* a1 = cA + (size_t)(t + 1) * kstep;
;     ...
;             PG8_LDA(At, 1, 1); PG8_STAGE(PG8_SB(1, 0), b3, voffB); PG8_STAGE(PG8_SB(1, 1), b3 + hstepB, voffB); PG8_STAGE(PG8_SA(1, 0), a3, voffA);
;             PG8_WAIT_V(8); PG8_WAIT_L(0); PG8_BAR; PG8_MMA(1, 0, At, B0); PG8_MMA(1, 1, At, B1); PG8_BAR; PG8_SCHED;
	s_add_i32 s10, s23, s19
	v_lshl_add_u64 v[208:209], v[208:209], 0, s[16:17]
	s_mov_b32 m0, s10
	ds_read_b128 v[176:179], v171 offset:49152
	ds_read_b128 v[180:183], v171 offset:50176
	ds_read_b128 v[184:187], v171 offset:51200
	ds_read_b128 v[188:191], v171 offset:52224
	ds_read_b128 v[192:195], v171 offset:53248
	ds_read_b128 v[196:199], v171 offset:54272
	ds_read_b128 v[200:203], v171 offset:55296
	ds_read_b128 v[204:207], v171 offset:56320
	global_load_lds_dwordx4 v[208:209], off
	s_add_i32 m0, s10, 0x2000
	s_add_u32 s10, s14, 0x160080
	v_lshl_add_u64 v[208:209], v[214:215], 0, s[16:17]
	s_addc_u32 s11, s15, 0
	s_add_i32 s14, s24, s19
	global_load_lds_dwordx4 v[208:209], off
	v_lshl_add_u64 v[208:209], s[10:11], 0, v[160:161]
	s_mov_b32 m0, s14
	s_nop 0
	global_load_lds_dwordx4 v[208:209], off
	v_lshl_add_u64 v[208:209], s[10:11], 0, v[162:163]
	s_add_i32 m0, s14, 0x2000
	s_nop 0
	global_load_lds_dwordx4 v[208:209], off
	v_lshl_add_u64 v[208:209], v[216:217], 0, s[16:17]
	s_mov_b32 m0, s41
	s_nop 0
	global_load_lds_dwordx4 v[208:209], off
	v_lshl_add_u64 v[208:209], v[218:219], 0, s[16:17]
	s_mov_b32 m0, s42
	s_nop 0
	global_load_lds_dwordx4 v[208:209], off
	s_waitcnt vmcnt(8)
	s_waitcnt lgkmcnt(0)
	s_barrier
	s_waitcnt lgkmcnt(0)
	v_mfma_f32_16x16x32_bf16 v[92:95], v[128:131], v[176:179], v[92:95]
	v_mfma_f32_16x16x32_bf16 v[92:95], v[132:135], v[180:183], v[92:95]
	v_mfma_f32_16x16x32_bf16 v[88:91], v[136:139], v[176:179], v[88:91]
	v_mfma_f32_16x16x32_bf16 v[88:91], v[140:143], v[180:183], v[88:91]
	v_mfma_f32_16x16x32_bf16 v[84:87], v[128:131], v[184:187], v[84:87]
	v_mfma_f32_16x16x32_bf16 v[84:87], v[132:135], v[188:191], v[84:87]
	v_mfma_f32_16x16x32_bf16 v[80:83], v[136:139], v[184:187], v[80:83]
	v_mfma_f32_16x16x32_bf16 v[80:83], v[140:143], v[188:191], v[80:83]
	v_mfma_f32_16x16x32_bf16 v[76:79], v[128:131], v[192:195], v[76:79]
	v_mfma_f32_16x16x32_bf16 v[76:79], v[132:135], v[196:199], v[76:79]
	v_mfma_f32_16x16x32_bf16 v[72:75], v[136:139], v[192:195], v[72:75]
	v_mfma_f32_16x16x32_bf16 v[72:75], v[140:143], v[196:199], v[72:75]
	v_mfma_f32_16x16x32_bf16 v[68:71], v[128:131], v[200:203], v[68:71]
	v_mfma_f32_16x16x32_bf16 v[68:71], v[132:135], v[204:207], v[68:71]
	v_mfma_f32_16x16x32_bf16 v[64:67], v[136:139], v[200:203], v[64:67]
	v_mfma_f32_16x16x32_bf16 v[64:67], v[140:143], v[204:207], v[64:67]
	v_mfma_f32_16x16x32_bf16 v[28:31], v[144:147], v[176:179], v[28:31]
	v_mfma_f32_16x16x32_bf16 v[28:31], v[148:151], v[180:183], v[28:31]
	v_mfma_f32_16x16x32_bf16 v[24:27], v[152:155], v[176:179], v[24:27]
	v_mfma_f32_16x16x32_bf16 v[24:27], v[172:175], v[180:183], v[24:27]
	v_mfma_f32_16x16x32_bf16 v[20:23], v[144:147], v[184:187], v[20:23]
	v_mfma_f32_16x16x32_bf16 v[20:23], v[148:151], v[188:191], v[20:23]
	v_mfma_f32_16x16x32_bf16 v[16:19], v[152:155], v[184:187], v[16:19]
	v_mfma_f32_16x16x32_bf16 v[16:19], v[172:175], v[188:191], v[16:19]
	v_mfma_f32_16x16x32_bf16 v[12:15], v[144:147], v[192:195], v[12:15]
	v_mfma_f32_16x16x32_bf16 v[12:15], v[148:151], v[196:199], v[12:15]
	v_mfma_f32_16x16x32_bf16 v[8:11], v[152:155], v[192:195], v[8:11]
	v_mfma_f32_16x16x32_bf16 v[8:11], v[172:175], v[196:199], v[8:11]
	v_mfma_f32_16x16x32_bf16 v[4:7], v[144:147], v[200:203], v[4:7]
	v_mfma_f32_16x16x32_bf16 v[4:7], v[148:151], v[204:207], v[4:7]
	v_mfma_f32_16x16x32_bf16 v[0:3], v[152:155], v[200:203], v[0:3]
	v_mfma_f32_16x16x32_bf16 v[0:3], v[172:175], v[204:207], v[0:3]
	s_barrier
	s_add_i32 s22, s22, 2
	s_add_u32 s20, s20, 0x100
	s_addc_u32 s21, s21, 0
	s_cmpk_gt_u32 s22, 0x55
	s_mov_b64 s[10:11], s[12:13]
